# speedup vs baseline: 1.0026x; 1.0026x over previous
; #define PG8_STAGE(bufoff, gbase, voff) do { _Pragma("unroll") for (int _i = 0; _i < 2; ++_i) \
;         __builtin_amdgcn_global_load_lds((const unsigned*)((const char*)(gbase) + (voff)[_i]), (PG8_LAS unsigned*)(lds + (bufoff) + ldsw + _i * 8192), 16, 0, 0); } while (0)
; #define PG8_LDA(dst, b, h) do { _Pragma("unroll") for (int m = 0; m < 4; ++m) _Pragma("unroll") for (int k = 0; k < 2; ++k) dst[m][k] = *(const PG8_LAS bf16x8*)(lds + PG8_SA(b, h) + aoff + m * 2048 + k * 1024); } while (0)
; #define PG8_LDB(dst, b, h) do { _Pragma("unroll") for (int n = 0; n < 2; ++n) _Pragma("unroll") for (int k = 0; k < 2; ++k) dst[n][k] = *(const PG8_LAS bf16x8*)(lds + PG8_SB(b, h) + boff + n * 2048 + k * 1024); } while (0)
; #define PG8_MMA(ai, bj, At, Bt) do { __builtin_amdgcn_s_setprio(1); _Pragma("unroll") for (int m = 0; m < 4; ++m) _Pragma("unroll") for (int n = 0; n < 2; ++n) _Pragma("unroll") for (int k = 0; k < 2; ++k) \
;         acc[ai][bj][m][n] = __builtin_amdgcn_mfma_f32_16x16x32_bf16(Bt[n][k], At[m][k], acc[ai][bj][m][n], 0, 0, 0); __builtin_amdgcn_s_setprio(0); } while (0)
; #define PG8_WAIT_V(n) asm volatile("s_waitcnt vmcnt(" #n ")" ::: "memory")
; #define PG8_WAIT_L(n) asm volatile("s_waitcnt lgkmcnt(" #n ")" ::: "memory")
; template <class Epi, class Sched, bool ALIGN_EPI = false, bool SP2 = false>
; __device__ __forceinline__ void gemm_phase(PG8_LAS unsigned char* lds, const Gemm g, const Sched& S, const Epi& E) {
;     ...
;             const bool last = (t == nt - 2);
;             const char* a1 = cA + (size_t)(t + 1) * kstep;
;             const char* a2 = last ? nA : cA + (size_t)(t + 2) * kstep; const char* b2 = last ? nB : cB + (size_t)(t + 2) * kstep;
;             const char* a3 = a2 + kstep; const char* b3 = b2 + kstep;
;             if (last && has_next) S.a_ready(nxt);
;             if constexpr (SP2) {
;             PG8_LDB(B0, 0, 0); PG8_LDB(B1, 0, 1); PG8_SCHED; PG8_LDA(At, 0, 0); PG8_STAGE(PG8_SA(1, 1), a1 + hstep, voffA);
;             PG8_WAIT_V(8); PG8_WAIT_L(0); PG8_BAR; PG8_MMA(0, 0, At, B0); PG8_MMA(0, 1, At, B1); PG8_BAR; PG8_SCHED;
;             PG8_LDA(At, 0, 1); PG8_STAGE(PG8_SB(0, 0), b2, voffB); PG8_STAGE(PG8_SB(0, 1), b2 + hstep, voffB); PG8_STAGE(PG8_SA(0, 0), a2, voffA);
;             PG8_WAIT_V(8); PG8_WAIT_L(0); PG8_BAR; PG8_MMA(1, 0, At, B0); PG8_MMA(1, 1, At, B1); PG8_BAR; PG8_SCHED;
.LBB0_129:
	v_add_u32_e32 v152, 0x10000, v178
	v_add_u32_e32 v168, 0x14000, v178
	ds_read_b128 v[128:131], v152
	ds_read_b128 v[132:135], v152 offset:1024
	ds_read_b128 v[148:151], v152 offset:2048
	ds_read_b128 v[152:155], v152 offset:3072
	ds_read_b128 v[156:159], v168
	ds_read_b128 v[160:163], v168 offset:1024
	ds_read_b128 v[164:167], v168 offset:2048
	ds_read_b128 v[168:171], v168 offset:3072
	v_lshl_add_u64 v[194:195], s[0:1], 0, v[144:145]
	s_add_i32 m0, s74, 0xc000
	ds_read_b128 v[172:175], v179
	ds_read_b128 v[180:183], v179 offset:1024
	ds_read_b128 v[184:187], v179 offset:2048
	ds_read_b128 v[188:191], v179 offset:3072
	ds_read_b128 v[206:209], v179 offset:4096
	ds_read_b128 v[210:213], v179 offset:5120
	ds_read_b128 v[214:217], v179 offset:6144
	ds_read_b128 v[218:221], v179 offset:7168
	global_load_lds_dwordx4 v[194:195], off
	s_add_i32 m0, s74, 0xe000
	v_lshl_add_u64 v[194:195], s[0:1], 0, v[146:147]
	global_load_lds_dwordx4 v[194:195], off
	s_add_u32 s12, s0, 0xfff80080
	s_addc_u32 s13, s1, -1
	s_add_i32 s43, 0, 0x10000
	s_cmp_eq_u32 s42, 28
	s_cselect_b32 s15, s2, s13
	s_cselect_b32 s14, s11, s12
	s_cselect_b32 s13, s18, s41
	s_cselect_b32 s12, s19, s34
	s_add_i32 s65, 0, 0x14000
	s_waitcnt vmcnt(8)
	s_waitcnt lgkmcnt(0)
	s_barrier
	s_setprio 1
	s_waitcnt lgkmcnt(0)
	v_mfma_f32_16x16x32_bf16 v[124:127], v[128:131], v[172:175], v[124:127]
	v_mfma_f32_16x16x32_bf16 v[120:123], v[148:151], v[172:175], v[120:123]
	v_mfma_f32_16x16x32_bf16 v[108:111], v[128:131], v[184:187], v[108:111]
	v_mfma_f32_16x16x32_bf16 v[104:107], v[148:151], v[184:187], v[104:107]
	v_mfma_f32_16x16x32_bf16 v[92:95], v[128:131], v[206:209], v[92:95]
	v_mfma_f32_16x16x32_bf16 v[88:91], v[148:151], v[206:209], v[88:91]
	v_mfma_f32_16x16x32_bf16 v[76:79], v[128:131], v[214:217], v[76:79]
	v_mfma_f32_16x16x32_bf16 v[72:75], v[148:151], v[214:217], v[72:75]
	v_mfma_f32_16x16x32_bf16 v[124:127], v[132:135], v[180:183], v[124:127]
	v_mfma_f32_16x16x32_bf16 v[120:123], v[152:155], v[180:183], v[120:123]
	v_mfma_f32_16x16x32_bf16 v[108:111], v[132:135], v[188:191], v[108:111]
	v_mfma_f32_16x16x32_bf16 v[104:107], v[152:155], v[188:191], v[104:107]
	v_mfma_f32_16x16x32_bf16 v[92:95], v[132:135], v[210:213], v[92:95]
	v_mfma_f32_16x16x32_bf16 v[88:91], v[152:155], v[210:213], v[88:91]
	v_mfma_f32_16x16x32_bf16 v[76:79], v[132:135], v[218:221], v[76:79]
	v_mfma_f32_16x16x32_bf16 v[72:75], v[152:155], v[218:221], v[72:75]
	s_setprio 0
	s_setprio 1
	v_mfma_f32_16x16x32_bf16 v[116:119], v[156:159], v[172:175], v[116:119]
	v_mfma_f32_16x16x32_bf16 v[112:115], v[164:167], v[172:175], v[112:115]
	v_mfma_f32_16x16x32_bf16 v[100:103], v[156:159], v[184:187], v[100:103]
	v_mfma_f32_16x16x32_bf16 v[96:99], v[164:167], v[184:187], v[96:99]
	v_mfma_f32_16x16x32_bf16 v[84:87], v[156:159], v[206:209], v[84:87]
	v_mfma_f32_16x16x32_bf16 v[80:83], v[164:167], v[206:209], v[80:83]
	v_mfma_f32_16x16x32_bf16 v[68:71], v[156:159], v[214:217], v[68:71]
	v_mfma_f32_16x16x32_bf16 v[64:67], v[164:167], v[214:217], v[64:67]
	v_mfma_f32_16x16x32_bf16 v[116:119], v[160:163], v[180:183], v[116:119]
	v_mfma_f32_16x16x32_bf16 v[112:115], v[168:171], v[180:183], v[112:115]
	v_mfma_f32_16x16x32_bf16 v[100:103], v[160:163], v[188:191], v[100:103]
	v_mfma_f32_16x16x32_bf16 v[96:99], v[168:171], v[188:191], v[96:99]
	v_mfma_f32_16x16x32_bf16 v[84:87], v[160:163], v[210:213], v[84:87]
	v_mfma_f32_16x16x32_bf16 v[80:83], v[168:171], v[210:213], v[80:83]
	v_mfma_f32_16x16x32_bf16 v[68:71], v[160:163], v[218:221], v[68:71]
	v_mfma_f32_16x16x32_bf16 v[64:67], v[168:171], v[218:221], v[64:67]
	s_setprio 0
	s_barrier
	s_add_i32 s43, s43, s39
	v_lshl_add_u64 v[194:195], s[12:13], 0, v[138:139]
	s_mov_b32 m0, s43
	ds_read_b128 v[172:175], v179 offset:16384
	ds_read_b128 v[180:183], v179 offset:17408
	ds_read_b128 v[184:187], v179 offset:18432
	ds_read_b128 v[188:191], v179 offset:19456
	ds_read_b128 v[206:209], v179 offset:20480
	ds_read_b128 v[210:213], v179 offset:21504
	ds_read_b128 v[214:217], v179 offset:22528
	ds_read_b128 v[218:221], v179 offset:23552
	global_load_lds_dwordx4 v[194:195], off
	s_add_i32 m0, s43, 0x2000
	s_add_u32 s86, s12, 0x80000
	v_lshl_add_u64 v[196:197], s[12:13], 0, v[142:143]
	s_addc_u32 s87, s13, 0
	s_add_i32 s43, s65, s39
	global_load_lds_dwordx4 v[196:197], off
	v_lshl_add_u64 v[202:203], s[86:87], 0, v[138:139]
	s_mov_b32 m0, s43
	v_lshl_add_u64 v[204:205], s[14:15], 0, v[140:141]
	global_load_lds_dwordx4 v[202:203], off
	s_add_i32 m0, s43, 0x2000
	v_lshl_add_u64 v[202:203], s[86:87], 0, v[142:143]
	global_load_lds_dwordx4 v[202:203], off
	s_mov_b32 m0, s74
	v_lshl_add_u64 v[202:203], s[14:15], 0, v[136:137]
	global_load_lds_dwordx4 v[202:203], off
	s_mov_b32 m0, s75
	s_nop 0
	global_load_lds_dwordx4 v[204:205], off
	s_waitcnt vmcnt(8)
	s_waitcnt lgkmcnt(0)
	s_barrier
; #define PG8_STAGE(bufoff, gbase, voff) do { _Pragma("unroll") for (int _i = 0; _i < 2; ++_i) \
;         __builtin_amdgcn_global_load_lds((const unsigned*)((const char*)(gbase) + (voff)[_i]), (PG8_LAS unsigned*)(lds + (bufoff) + ldsw + _i * 8192), 16, 0, 0); } while (0)
; #define PG8_LDA(dst, b, h) do { _Pragma("unroll") for (int m = 0; m < 4; ++m) _Pragma("unroll") for (int k = 0; k < 2; ++k) dst[m][k] = *(const PG8_LAS bf16x8*)(lds + PG8_SA(b, h) + aoff + m * 2048 + k * 1024); } while (0)
; #define PG8_LDB(dst, b, h) do { _Pragma("unroll") for (int n = 0; n < 2; ++n) _Pragma("unroll") for (int k = 0; k < 2; ++k) dst[n][k] = *(const PG8_LAS bf16x8*)(lds + PG8_SB(b, h) + boff + n * 2048 + k * 1024); } while (0)
; #define PG8_MMA(ai, bj, At, Bt) do { __builtin_amdgcn_s_setprio(1); _Pragma("unroll") for (int m = 0; m < 4; ++m) _Pragma("unroll") for (int n = 0; n < 2; ++n) _Pragma("unroll") for (int k = 0; k < 2; ++k) \
;         acc[ai][bj][m][n] = __builtin_amdgcn_mfma_f32_16x16x32_bf16(Bt[n][k], At[m][k], acc[ai][bj][m][n], 0, 0, 0); __builtin_amdgcn_s_setprio(0); } while (0)
; #define PG8_WAIT_V(n) asm volatile("s_waitcnt vmcnt(" #n ")" ::: "memory")
; #define PG8_WAIT_L(n) asm volatile("s_waitcnt lgkmcnt(" #n ")" ::: "memory")
; #define PG8_BAR __builtin_amdgcn_s_barrier()
; #define PG8_SCHED __builtin_amdgcn_sched_barrier(0)
; template <class Epi, class Sched, bool ALIGN_EPI = false, bool SP2 = false>
; __device__ __forceinline__ void gemm_phase(PG8_LAS unsigned char* lds, const Gemm g, const Sched& S, const Epi& E) {
;     ...
;             PG8_LDA(At, 0, 1); PG8_STAGE(PG8_SB(0, 0), b2, voffB); PG8_STAGE(PG8_SB(0, 1), b2 + hstep, voffB); PG8_STAGE(PG8_SA(0, 0), a2, voffA);
;             PG8_WAIT_V(8); PG8_WAIT_L(0); PG8_BAR; PG8_MMA(1, 0, At, B0); PG8_MMA(1, 1, At, B1); PG8_BAR; PG8_SCHED;
;             PG8_LDB(B0, 1, 0); PG8_LDB(B1, 1, 1); PG8_SCHED; PG8_LDA(At, 1, 0); PG8_STAGE(PG8_SA(0, 1), a2 + hstep, voffA);
;             PG8_WAIT_V(8); PG8_WAIT_L(0); PG8_BAR; PG8_MMA(0, 0, At, B0); PG8_MMA(0, 1, At, B1); PG8_BAR; PG8_SCHED;
;             PG8_LDA(At, 1, 1); PG8_STAGE(PG8_SB(1, 0), b3, voffB); PG8_STAGE(PG8_SB(1, 1), b3 + hstep, voffB); PG8_STAGE(PG8_SA(1, 0), a3, voffA);
	s_setprio 1
	s_waitcnt lgkmcnt(0)
	v_mfma_f32_16x16x32_bf16 v[60:63], v[128:131], v[172:175], v[60:63]
	v_mfma_f32_16x16x32_bf16 v[56:59], v[148:151], v[172:175], v[56:59]
	v_mfma_f32_16x16x32_bf16 v[44:47], v[128:131], v[184:187], v[44:47]
	v_mfma_f32_16x16x32_bf16 v[40:43], v[148:151], v[184:187], v[40:43]
	v_mfma_f32_16x16x32_bf16 v[28:31], v[128:131], v[206:209], v[28:31]
	v_mfma_f32_16x16x32_bf16 v[24:27], v[148:151], v[206:209], v[24:27]
	v_mfma_f32_16x16x32_bf16 v[12:15], v[128:131], v[214:217], v[12:15]
	v_mfma_f32_16x16x32_bf16 v[8:11], v[148:151], v[214:217], v[8:11]
	v_mfma_f32_16x16x32_bf16 v[60:63], v[132:135], v[180:183], v[60:63]
	v_mfma_f32_16x16x32_bf16 v[56:59], v[152:155], v[180:183], v[56:59]
	v_mfma_f32_16x16x32_bf16 v[44:47], v[132:135], v[188:191], v[44:47]
	v_mfma_f32_16x16x32_bf16 v[40:43], v[152:155], v[188:191], v[40:43]
	v_mfma_f32_16x16x32_bf16 v[28:31], v[132:135], v[210:213], v[28:31]
	v_mfma_f32_16x16x32_bf16 v[24:27], v[152:155], v[210:213], v[24:27]
	v_mfma_f32_16x16x32_bf16 v[12:15], v[132:135], v[218:221], v[12:15]
	v_mfma_f32_16x16x32_bf16 v[8:11], v[152:155], v[218:221], v[8:11]
	s_setprio 0
	s_setprio 1
	v_mfma_f32_16x16x32_bf16 v[52:55], v[156:159], v[172:175], v[52:55]
	v_mfma_f32_16x16x32_bf16 v[48:51], v[164:167], v[172:175], v[48:51]
	v_mfma_f32_16x16x32_bf16 v[36:39], v[156:159], v[184:187], v[36:39]
	v_mfma_f32_16x16x32_bf16 v[32:35], v[164:167], v[184:187], v[32:35]
	v_mfma_f32_16x16x32_bf16 v[20:23], v[156:159], v[206:209], v[20:23]
	v_mfma_f32_16x16x32_bf16 v[16:19], v[164:167], v[206:209], v[16:19]
	v_mfma_f32_16x16x32_bf16 v[4:7], v[156:159], v[214:217], v[4:7]
	v_mfma_f32_16x16x32_bf16 v[0:3], v[164:167], v[214:217], v[0:3]
	v_mfma_f32_16x16x32_bf16 v[52:55], v[160:163], v[180:183], v[52:55]
	v_mfma_f32_16x16x32_bf16 v[48:51], v[168:171], v[180:183], v[48:51]
	v_mfma_f32_16x16x32_bf16 v[36:39], v[160:163], v[188:191], v[36:39]
	v_mfma_f32_16x16x32_bf16 v[32:35], v[168:171], v[188:191], v[32:35]
	v_mfma_f32_16x16x32_bf16 v[20:23], v[160:163], v[210:213], v[20:23]
	v_mfma_f32_16x16x32_bf16 v[16:19], v[168:171], v[210:213], v[16:19]
	v_mfma_f32_16x16x32_bf16 v[4:7], v[160:163], v[218:221], v[4:7]
	v_mfma_f32_16x16x32_bf16 v[0:3], v[168:171], v[218:221], v[0:3]
	s_setprio 0
	s_barrier
	s_add_i32 s43, 0, 0x18000
	s_add_i32 s65, 0, 0x1c000
	v_add_u32_e32 v152, 0x18000, v178
	v_add_u32_e32 v168, 0x1c000, v178
	ds_read_b128 v[128:131], v152
	ds_read_b128 v[132:135], v152 offset:1024
	ds_read_b128 v[148:151], v152 offset:2048
	ds_read_b128 v[152:155], v152 offset:3072
	ds_read_b128 v[156:159], v168
	ds_read_b128 v[160:163], v168 offset:1024
	ds_read_b128 v[164:167], v168 offset:2048
	ds_read_b128 v[168:171], v168 offset:3072
	s_add_u32 s14, s14, 0x80000
	s_addc_u32 s15, s15, 0
	s_mov_b32 m0, s76
	v_lshl_add_u64 v[232:233], s[14:15], 0, v[136:137]
	ds_read_b128 v[172:175], v179 offset:32768
	ds_read_b128 v[180:183], v179 offset:33792
	ds_read_b128 v[184:187], v179 offset:34816
	ds_read_b128 v[188:191], v179 offset:35840
	ds_read_b128 v[206:209], v179 offset:36864
	ds_read_b128 v[210:213], v179 offset:37888
	ds_read_b128 v[214:217], v179 offset:38912
	ds_read_b128 v[218:221], v179 offset:39936
	global_load_lds_dwordx4 v[232:233], off
	s_mov_b32 m0, s77
	v_lshl_add_u64 v[232:233], s[14:15], 0, v[140:141]
	global_load_lds_dwordx4 v[232:233], off
	s_waitcnt vmcnt(8)
	s_waitcnt lgkmcnt(0)
	s_barrier
	s_setprio 1
	s_waitcnt lgkmcnt(0)
	v_mfma_f32_16x16x32_bf16 v[124:127], v[128:131], v[172:175], v[124:127]
	v_mfma_f32_16x16x32_bf16 v[120:123], v[148:151], v[172:175], v[120:123]
	v_mfma_f32_16x16x32_bf16 v[108:111], v[128:131], v[184:187], v[108:111]
	v_mfma_f32_16x16x32_bf16 v[104:107], v[148:151], v[184:187], v[104:107]
	v_mfma_f32_16x16x32_bf16 v[92:95], v[128:131], v[206:209], v[92:95]
	v_mfma_f32_16x16x32_bf16 v[88:91], v[148:151], v[206:209], v[88:91]
	v_mfma_f32_16x16x32_bf16 v[76:79], v[128:131], v[214:217], v[76:79]
	v_mfma_f32_16x16x32_bf16 v[72:75], v[148:151], v[214:217], v[72:75]
	v_mfma_f32_16x16x32_bf16 v[124:127], v[132:135], v[180:183], v[124:127]
	v_mfma_f32_16x16x32_bf16 v[120:123], v[152:155], v[180:183], v[120:123]
	v_mfma_f32_16x16x32_bf16 v[108:111], v[132:135], v[188:191], v[108:111]
	v_mfma_f32_16x16x32_bf16 v[104:107], v[152:155], v[188:191], v[104:107]
	v_mfma_f32_16x16x32_bf16 v[92:95], v[132:135], v[210:213], v[92:95]
	v_mfma_f32_16x16x32_bf16 v[88:91], v[152:155], v[210:213], v[88:91]
	v_mfma_f32_16x16x32_bf16 v[76:79], v[132:135], v[218:221], v[76:79]
	v_mfma_f32_16x16x32_bf16 v[72:75], v[152:155], v[218:221], v[72:75]
	s_setprio 0
	s_setprio 1
	v_mfma_f32_16x16x32_bf16 v[116:119], v[156:159], v[172:175], v[116:119]
	v_mfma_f32_16x16x32_bf16 v[112:115], v[164:167], v[172:175], v[112:115]
	v_mfma_f32_16x16x32_bf16 v[100:103], v[156:159], v[184:187], v[100:103]
	v_mfma_f32_16x16x32_bf16 v[96:99], v[164:167], v[184:187], v[96:99]
	v_mfma_f32_16x16x32_bf16 v[84:87], v[156:159], v[206:209], v[84:87]
	v_mfma_f32_16x16x32_bf16 v[80:83], v[164:167], v[206:209], v[80:83]
	v_mfma_f32_16x16x32_bf16 v[68:71], v[156:159], v[214:217], v[68:71]
	v_mfma_f32_16x16x32_bf16 v[64:67], v[164:167], v[214:217], v[64:67]
	v_mfma_f32_16x16x32_bf16 v[116:119], v[160:163], v[180:183], v[116:119]
	v_mfma_f32_16x16x32_bf16 v[112:115], v[168:171], v[180:183], v[112:115]
	v_mfma_f32_16x16x32_bf16 v[100:103], v[160:163], v[188:191], v[100:103]
	v_mfma_f32_16x16x32_bf16 v[96:99], v[168:171], v[188:191], v[96:99]
	v_mfma_f32_16x16x32_bf16 v[84:87], v[160:163], v[210:213], v[84:87]
	v_mfma_f32_16x16x32_bf16 v[80:83], v[168:171], v[210:213], v[80:83]
	v_mfma_f32_16x16x32_bf16 v[68:71], v[160:163], v[218:221], v[68:71]
	v_mfma_f32_16x16x32_bf16 v[64:67], v[168:171], v[218:221], v[64:67]
	s_setprio 0
	s_barrier
; #define PG8_STAGE(bufoff, gbase, voff) do { _Pragma("unroll") for (int _i = 0; _i < 2; ++_i) \
;         __builtin_amdgcn_global_load_lds((const unsigned*)((const char*)(gbase) + (voff)[_i]), (PG8_LAS unsigned*)(lds + (bufoff) + ldsw + _i * 8192), 16, 0, 0); } while (0)
; #define PG8_LDA(dst, b, h) do { _Pragma("unroll") for (int m = 0; m < 4; ++m) _Pragma("unroll") for (int k = 0; k < 2; ++k) dst[m][k] = *(const PG8_LAS bf16x8*)(lds + PG8_SA(b, h) + aoff + m * 2048 + k * 1024); } while (0)
; #define PG8_MMA(ai, bj, At, Bt) do { __builtin_amdgcn_s_setprio(1); _Pragma("unroll") for (int m = 0; m < 4; ++m) _Pragma("unroll") for (int n = 0; n < 2; ++n) _Pragma("unroll") for (int k = 0; k < 2; ++k) \
;         acc[ai][bj][m][n] = __builtin_amdgcn_mfma_f32_16x16x32_bf16(Bt[n][k], At[m][k], acc[ai][bj][m][n], 0, 0, 0); __builtin_amdgcn_s_setprio(0); } while (0)
; #define PG8_WAIT_V(n) asm volatile("s_waitcnt vmcnt(" #n ")" ::: "memory")
; #define PG8_WAIT_L(n) asm volatile("s_waitcnt lgkmcnt(" #n ")" ::: "memory")
; #define PG8_BAR __builtin_amdgcn_s_barrier()
; #define PG8_SCHED __builtin_amdgcn_sched_barrier(0)
; template <class Epi, class Sched, bool ALIGN_EPI = false, bool SP2 = false>
; __device__ __forceinline__ void gemm_phase(PG8_LAS unsigned char* lds, const Gemm g, const Sched& S, const Epi& E) {
;     ...
;         for (int t = 0; t < nt; t += 2) {
;     ...
;             PG8_WAIT_V(8); PG8_WAIT_L(0); PG8_BAR; PG8_MMA(0, 0, At, B0); PG8_MMA(0, 1, At, B1); PG8_BAR; PG8_SCHED;
;             PG8_LDA(At, 1, 1); PG8_STAGE(PG8_SB(1, 0), b3, voffB); PG8_STAGE(PG8_SB(1, 1), b3 + hstep, voffB); PG8_STAGE(PG8_SA(1, 0), a3, voffA);
;             PG8_WAIT_V(8); PG8_WAIT_L(0); PG8_BAR; PG8_MMA(1, 0, At, B0); PG8_MMA(1, 1, At, B1); PG8_BAR; PG8_SCHED;
	s_add_i32 s14, s43, s39
	v_lshl_add_u64 v[194:195], v[194:195], 0, s[16:17]
	s_mov_b32 m0, s14
	ds_read_b128 v[172:175], v179 offset:49152
	ds_read_b128 v[180:183], v179 offset:50176
	ds_read_b128 v[184:187], v179 offset:51200
	ds_read_b128 v[188:191], v179 offset:52224
	ds_read_b128 v[206:209], v179 offset:53248
	ds_read_b128 v[210:213], v179 offset:54272
	ds_read_b128 v[214:217], v179 offset:55296
	ds_read_b128 v[218:221], v179 offset:56320
	global_load_lds_dwordx4 v[194:195], off
	s_add_i32 m0, s14, 0x2000
	s_add_u32 s12, s12, 0x80080
	v_lshl_add_u64 v[194:195], v[196:197], 0, s[16:17]
	s_addc_u32 s13, s13, 0
	s_add_i32 s14, s65, s39
	global_load_lds_dwordx4 v[194:195], off
	s_mov_b32 m0, s14
	v_lshl_add_u64 v[194:195], s[12:13], 0, v[138:139]
	global_load_lds_dwordx4 v[194:195], off
	s_add_i32 m0, s14, 0x2000
	v_lshl_add_u64 v[194:195], s[12:13], 0, v[142:143]
	global_load_lds_dwordx4 v[194:195], off
	s_mov_b32 m0, s80
	v_lshl_add_u64 v[194:195], v[202:203], 0, s[16:17]
	global_load_lds_dwordx4 v[194:195], off
	s_mov_b32 m0, s81
	v_lshl_add_u64 v[194:195], v[204:205], 0, s[16:17]
	global_load_lds_dwordx4 v[194:195], off
	s_waitcnt vmcnt(8)
	s_waitcnt lgkmcnt(0)
	s_barrier
	s_setprio 1
	s_waitcnt lgkmcnt(0)
	v_mfma_f32_16x16x32_bf16 v[60:63], v[128:131], v[172:175], v[60:63]
	v_mfma_f32_16x16x32_bf16 v[56:59], v[148:151], v[172:175], v[56:59]
	v_mfma_f32_16x16x32_bf16 v[44:47], v[128:131], v[184:187], v[44:47]
	v_mfma_f32_16x16x32_bf16 v[40:43], v[148:151], v[184:187], v[40:43]
	v_mfma_f32_16x16x32_bf16 v[28:31], v[128:131], v[206:209], v[28:31]
	v_mfma_f32_16x16x32_bf16 v[24:27], v[148:151], v[206:209], v[24:27]
	v_mfma_f32_16x16x32_bf16 v[12:15], v[128:131], v[214:217], v[12:15]
	v_mfma_f32_16x16x32_bf16 v[8:11], v[148:151], v[214:217], v[8:11]
	v_mfma_f32_16x16x32_bf16 v[60:63], v[132:135], v[180:183], v[60:63]
	v_mfma_f32_16x16x32_bf16 v[56:59], v[152:155], v[180:183], v[56:59]
	v_mfma_f32_16x16x32_bf16 v[44:47], v[132:135], v[188:191], v[44:47]
	v_mfma_f32_16x16x32_bf16 v[40:43], v[152:155], v[188:191], v[40:43]
	v_mfma_f32_16x16x32_bf16 v[28:31], v[132:135], v[210:213], v[28:31]
	v_mfma_f32_16x16x32_bf16 v[24:27], v[152:155], v[210:213], v[24:27]
	v_mfma_f32_16x16x32_bf16 v[12:15], v[132:135], v[218:221], v[12:15]
	v_mfma_f32_16x16x32_bf16 v[8:11], v[152:155], v[218:221], v[8:11]
	s_setprio 0
	s_setprio 1
	v_mfma_f32_16x16x32_bf16 v[52:55], v[156:159], v[172:175], v[52:55]
	v_mfma_f32_16x16x32_bf16 v[48:51], v[164:167], v[172:175], v[48:51]
	v_mfma_f32_16x16x32_bf16 v[36:39], v[156:159], v[184:187], v[36:39]
	v_mfma_f32_16x16x32_bf16 v[32:35], v[164:167], v[184:187], v[32:35]
	v_mfma_f32_16x16x32_bf16 v[20:23], v[156:159], v[206:209], v[20:23]
	v_mfma_f32_16x16x32_bf16 v[16:19], v[164:167], v[206:209], v[16:19]
	v_mfma_f32_16x16x32_bf16 v[4:7], v[156:159], v[214:217], v[4:7]
	v_mfma_f32_16x16x32_bf16 v[0:3], v[164:167], v[214:217], v[0:3]
	v_mfma_f32_16x16x32_bf16 v[52:55], v[160:163], v[180:183], v[52:55]
	v_mfma_f32_16x16x32_bf16 v[48:51], v[168:171], v[180:183], v[48:51]
	v_mfma_f32_16x16x32_bf16 v[36:39], v[160:163], v[188:191], v[36:39]
	v_mfma_f32_16x16x32_bf16 v[32:35], v[168:171], v[188:191], v[32:35]
	v_mfma_f32_16x16x32_bf16 v[20:23], v[160:163], v[210:213], v[20:23]
	v_mfma_f32_16x16x32_bf16 v[16:19], v[168:171], v[210:213], v[16:19]
	v_mfma_f32_16x16x32_bf16 v[4:7], v[160:163], v[218:221], v[4:7]
	v_mfma_f32_16x16x32_bf16 v[0:3], v[168:171], v[218:221], v[0:3]
	s_setprio 0
	s_barrier
	s_add_i32 s42, s42, 2
	s_add_u32 s0, s0, 0x100
	s_addc_u32 s1, s1, 0
	s_add_u32 s34, s34, 0x100
	s_addc_u32 s41, s41, 0
	s_cmp_gt_u32 s42, 29
	s_cbranch_scc0 .LBB0_129
	s_and_b64 vcc, exec, s[62:63]
	s_cbranch_vccz .LBB0_132
	s_barrier

; #define PG8_STAGE(bufoff, gbase, voff) do { _Pragma("unroll") for (int _i = 0; _i < 2; ++_i) \
;         __builtin_amdgcn_global_load_lds((const unsigned*)((const char*)(gbase) + (voff)[_i]), (PG8_LAS unsigned*)(lds + (bufoff) + ldsw + _i * 8192), 16, 0, 0); } while (0)
; #define PG8_LDA(dst, b, h) do { _Pragma("unroll") for (int m = 0; m < 4; ++m) _Pragma("unroll") for (int k = 0; k < 2; ++k) dst[m][k] = *(const PG8_LAS bf16x8*)(lds + PG8_SA(b, h) + aoff + m * 2048 + k * 1024); } while (0)
; #define PG8_LDB(dst, b, h) do { _Pragma("unroll") for (int n = 0; n < 2; ++n) _Pragma("unroll") for (int k = 0; k < 2; ++k) dst[n][k] = *(const PG8_LAS bf16x8*)(lds + PG8_SB(b, h) + boff + n * 2048 + k * 1024); } while (0)
; #define PG8_MMA(ai, bj, At, Bt) do { __builtin_amdgcn_s_setprio(1); _Pragma("unroll") for (int m = 0; m < 4; ++m) _Pragma("unroll") for (int n = 0; n < 2; ++n) _Pragma("unroll") for (int k = 0; k < 2; ++k) \
;         acc[ai][bj][m][n] = __builtin_amdgcn_mfma_f32_16x16x32_bf16(Bt[n][k], At[m][k], acc[ai][bj][m][n], 0, 0, 0); __builtin_amdgcn_s_setprio(0); } while (0)
; #define PG8_WAIT_V(n) asm volatile("s_waitcnt vmcnt(" #n ")" ::: "memory")
; #define PG8_WAIT_L(n) asm volatile("s_waitcnt lgkmcnt(" #n ")" ::: "memory")
; template <class Epi, class Sched, bool ALIGN_EPI = false, bool SP2 = false>
; __device__ __forceinline__ void gemm_phase(PG8_LAS unsigned char* lds, const Gemm g, const Sched& S, const Epi& E) {
;     ...
;             const bool last = (t == nt - 2);
;             const char* a1 = cA + (size_t)(t + 1) * kstep;
;             const char* a2 = last ? nA : cA + (size_t)(t + 2) * kstep; const char* b2 = last ? nB : cB + (size_t)(t + 2) * kstep;
;             const char* a3 = a2 + kstep; const char* b3 = b2 + kstep;
;             if (last && has_next) S.a_ready(nxt);
;             if constexpr (SP2) {
;             PG8_LDB(B0, 0, 0); PG8_LDB(B1, 0, 1); PG8_SCHED; PG8_LDA(At, 0, 0); PG8_STAGE(PG8_SA(1, 1), a1 + hstep, voffA);
;             PG8_WAIT_V(8); PG8_WAIT_L(0); PG8_BAR; PG8_MMA(0, 0, At, B0); PG8_MMA(0, 1, At, B1); PG8_BAR; PG8_SCHED;
;             PG8_LDA(At, 0, 1); PG8_STAGE(PG8_SB(0, 0), b2, voffB); PG8_STAGE(PG8_SB(0, 1), b2 + hstep, voffB); PG8_STAGE(PG8_SA(0, 0), a2, voffA);
;             PG8_WAIT_V(8); PG8_WAIT_L(0); PG8_BAR; PG8_MMA(1, 0, At, B0); PG8_MMA(1, 1, At, B1); PG8_BAR; PG8_SCHED;
.LBB0_635:
	v_add_u32_e32 v140, 0x10000, v172
	v_add_u32_e32 v168, 0x14000, v172
	ds_read_b128 v[128:131], v140
	ds_read_b128 v[132:135], v140 offset:1024
	ds_read_b128 v[136:139], v140 offset:2048
	ds_read_b128 v[140:143], v140 offset:3072
	ds_read_b128 v[144:147], v168
	ds_read_b128 v[148:151], v168 offset:1024
	ds_read_b128 v[164:167], v168 offset:2048
	ds_read_b128 v[174:177], v168 offset:3072
	v_lshl_add_u64 v[168:169], s[36:37], 0, v[160:161]
	s_add_i32 m0, s2, 0xc000
	ds_read_b128 v[178:181], v173
	ds_read_b128 v[182:185], v173 offset:1024
	ds_read_b128 v[186:189], v173 offset:2048
	ds_read_b128 v[194:197], v173 offset:3072
	ds_read_b128 v[202:205], v173 offset:4096
	ds_read_b128 v[206:209], v173 offset:5120
	ds_read_b128 v[210:213], v173 offset:6144
	ds_read_b128 v[214:217], v173 offset:7168
	global_load_lds_dwordx4 v[168:169], off
	s_add_i32 m0, s2, 0xe000
	v_lshl_add_u64 v[168:169], s[36:37], 0, v[162:163]
	global_load_lds_dwordx4 v[168:169], off
	s_add_u32 s24, s36, 0xfff80080
	s_addc_u32 s25, s37, -1
	s_add_i32 s33, 0, 0x10000
	s_cmp_eq_u32 s65, 28
	s_cselect_b32 s43, s15, s25
	s_cselect_b32 s42, s61, s24
	s_cselect_b32 s39, s13, s64
	s_cselect_b32 s38, s62, s63
	s_add_i32 s24, 0, 0x14000
	s_waitcnt vmcnt(8)
	s_waitcnt lgkmcnt(0)
	s_barrier
	s_setprio 1
	s_waitcnt lgkmcnt(0)
	v_mfma_f32_16x16x32_bf16 v[124:127], v[128:131], v[178:181], v[124:127]
	v_mfma_f32_16x16x32_bf16 v[120:123], v[136:139], v[178:181], v[120:123]
	v_mfma_f32_16x16x32_bf16 v[108:111], v[128:131], v[186:189], v[108:111]
	v_mfma_f32_16x16x32_bf16 v[104:107], v[136:139], v[186:189], v[104:107]
	v_mfma_f32_16x16x32_bf16 v[92:95], v[128:131], v[202:205], v[92:95]
	v_mfma_f32_16x16x32_bf16 v[88:91], v[136:139], v[202:205], v[88:91]
	v_mfma_f32_16x16x32_bf16 v[76:79], v[128:131], v[210:213], v[76:79]
	v_mfma_f32_16x16x32_bf16 v[72:75], v[136:139], v[210:213], v[72:75]
	v_mfma_f32_16x16x32_bf16 v[124:127], v[132:135], v[182:185], v[124:127]
	v_mfma_f32_16x16x32_bf16 v[120:123], v[140:143], v[182:185], v[120:123]
	v_mfma_f32_16x16x32_bf16 v[108:111], v[132:135], v[194:197], v[108:111]
	v_mfma_f32_16x16x32_bf16 v[104:107], v[140:143], v[194:197], v[104:107]
	v_mfma_f32_16x16x32_bf16 v[92:95], v[132:135], v[206:209], v[92:95]
	v_mfma_f32_16x16x32_bf16 v[88:91], v[140:143], v[206:209], v[88:91]
	v_mfma_f32_16x16x32_bf16 v[76:79], v[132:135], v[214:217], v[76:79]
	v_mfma_f32_16x16x32_bf16 v[72:75], v[140:143], v[214:217], v[72:75]
	s_setprio 0
	s_setprio 1
	v_mfma_f32_16x16x32_bf16 v[116:119], v[144:147], v[178:181], v[116:119]
	v_mfma_f32_16x16x32_bf16 v[112:115], v[164:167], v[178:181], v[112:115]
	v_mfma_f32_16x16x32_bf16 v[100:103], v[144:147], v[186:189], v[100:103]
	v_mfma_f32_16x16x32_bf16 v[96:99], v[164:167], v[186:189], v[96:99]
	v_mfma_f32_16x16x32_bf16 v[84:87], v[144:147], v[202:205], v[84:87]
	v_mfma_f32_16x16x32_bf16 v[80:83], v[164:167], v[202:205], v[80:83]
	v_mfma_f32_16x16x32_bf16 v[68:71], v[144:147], v[210:213], v[68:71]
	v_mfma_f32_16x16x32_bf16 v[64:67], v[164:167], v[210:213], v[64:67]
	v_mfma_f32_16x16x32_bf16 v[116:119], v[148:151], v[182:185], v[116:119]
	v_mfma_f32_16x16x32_bf16 v[112:115], v[174:177], v[182:185], v[112:115]
	v_mfma_f32_16x16x32_bf16 v[100:103], v[148:151], v[194:197], v[100:103]
	v_mfma_f32_16x16x32_bf16 v[96:99], v[174:177], v[194:197], v[96:99]
	v_mfma_f32_16x16x32_bf16 v[84:87], v[148:151], v[206:209], v[84:87]
	v_mfma_f32_16x16x32_bf16 v[80:83], v[174:177], v[206:209], v[80:83]
	v_mfma_f32_16x16x32_bf16 v[68:71], v[148:151], v[214:217], v[68:71]
	v_mfma_f32_16x16x32_bf16 v[64:67], v[174:177], v[214:217], v[64:67]
	s_setprio 0
	s_barrier
	s_add_i32 s25, s33, s47
	v_lshl_add_u64 v[168:169], s[38:39], 0, v[156:157]
	s_mov_b32 m0, s25
	ds_read_b128 v[178:181], v173 offset:16384
	ds_read_b128 v[182:185], v173 offset:17408
	ds_read_b128 v[186:189], v173 offset:18432
	ds_read_b128 v[194:197], v173 offset:19456
	ds_read_b128 v[202:205], v173 offset:20480
	ds_read_b128 v[206:209], v173 offset:21504
	ds_read_b128 v[210:213], v173 offset:22528
	ds_read_b128 v[214:217], v173 offset:23552
	global_load_lds_dwordx4 v[168:169], off
	s_add_i32 m0, s25, 0x2000
	s_add_u32 s66, s38, 0x80000
	v_lshl_add_u64 v[190:191], s[38:39], 0, v[152:153]
	s_addc_u32 s67, s39, 0
	s_add_i32 s24, s24, s47
	global_load_lds_dwordx4 v[190:191], off
	v_lshl_add_u64 v[218:219], s[66:67], 0, v[156:157]
	s_mov_b32 m0, s24
	v_lshl_add_u64 v[220:221], s[42:43], 0, v[154:155]
	global_load_lds_dwordx4 v[218:219], off
	s_add_i32 m0, s24, 0x2000
	v_lshl_add_u64 v[218:219], s[66:67], 0, v[152:153]
	global_load_lds_dwordx4 v[218:219], off
	s_mov_b32 m0, s2
	v_lshl_add_u64 v[218:219], s[42:43], 0, v[158:159]
	global_load_lds_dwordx4 v[218:219], off
	s_mov_b32 m0, s48
	s_nop 0
	global_load_lds_dwordx4 v[220:221], off
	s_waitcnt vmcnt(8)
	s_waitcnt lgkmcnt(0)
	s_barrier
; #define PG8_STAGE(bufoff, gbase, voff) do { _Pragma("unroll") for (int _i = 0; _i < 2; ++_i) \
;         __builtin_amdgcn_global_load_lds((const unsigned*)((const char*)(gbase) + (voff)[_i]), (PG8_LAS unsigned*)(lds + (bufoff) + ldsw + _i * 8192), 16, 0, 0); } while (0)
; #define PG8_LDA(dst, b, h) do { _Pragma("unroll") for (int m = 0; m < 4; ++m) _Pragma("unroll") for (int k = 0; k < 2; ++k) dst[m][k] = *(const PG8_LAS bf16x8*)(lds + PG8_SA(b, h) + aoff + m * 2048 + k * 1024); } while (0)
; #define PG8_LDB(dst, b, h) do { _Pragma("unroll") for (int n = 0; n < 2; ++n) _Pragma("unroll") for (int k = 0; k < 2; ++k) dst[n][k] = *(const PG8_LAS bf16x8*)(lds + PG8_SB(b, h) + boff + n * 2048 + k * 1024); } while (0)
; #define PG8_MMA(ai, bj, At, Bt) do { __builtin_amdgcn_s_setprio(1); _Pragma("unroll") for (int m = 0; m < 4; ++m) _Pragma("unroll") for (int n = 0; n < 2; ++n) _Pragma("unroll") for (int k = 0; k < 2; ++k) \
;         acc[ai][bj][m][n] = __builtin_amdgcn_mfma_f32_16x16x32_bf16(Bt[n][k], At[m][k], acc[ai][bj][m][n], 0, 0, 0); __builtin_amdgcn_s_setprio(0); } while (0)
; #define PG8_WAIT_V(n) asm volatile("s_waitcnt vmcnt(" #n ")" ::: "memory")
; #define PG8_WAIT_L(n) asm volatile("s_waitcnt lgkmcnt(" #n ")" ::: "memory")
; #define PG8_BAR __builtin_amdgcn_s_barrier()
; #define PG8_SCHED __builtin_amdgcn_sched_barrier(0)
; template <class Epi, class Sched, bool ALIGN_EPI = false, bool SP2 = false>
; __device__ __forceinline__ void gemm_phase(PG8_LAS unsigned char* lds, const Gemm g, const Sched& S, const Epi& E) {
;     ...
;             PG8_LDA(At, 0, 1); PG8_STAGE(PG8_SB(0, 0), b2, voffB); PG8_STAGE(PG8_SB(0, 1), b2 + hstep, voffB); PG8_STAGE(PG8_SA(0, 0), a2, voffA);
;             PG8_WAIT_V(8); PG8_WAIT_L(0); PG8_BAR; PG8_MMA(1, 0, At, B0); PG8_MMA(1, 1, At, B1); PG8_BAR; PG8_SCHED;
;             PG8_LDB(B0, 1, 0); PG8_LDB(B1, 1, 1); PG8_SCHED; PG8_LDA(At, 1, 0); PG8_STAGE(PG8_SA(0, 1), a2 + hstep, voffA);
;             PG8_WAIT_V(8); PG8_WAIT_L(0); PG8_BAR; PG8_MMA(0, 0, At, B0); PG8_MMA(0, 1, At, B1); PG8_BAR; PG8_SCHED;
;             PG8_LDA(At, 1, 1); PG8_STAGE(PG8_SB(1, 0), b3, voffB); PG8_STAGE(PG8_SB(1, 1), b3 + hstep, voffB); PG8_STAGE(PG8_SA(1, 0), a3, voffA);
	s_setprio 1
	s_waitcnt lgkmcnt(0)
	v_mfma_f32_16x16x32_bf16 v[60:63], v[128:131], v[178:181], v[60:63]
	v_mfma_f32_16x16x32_bf16 v[56:59], v[136:139], v[178:181], v[56:59]
	v_mfma_f32_16x16x32_bf16 v[44:47], v[128:131], v[186:189], v[44:47]
	v_mfma_f32_16x16x32_bf16 v[40:43], v[136:139], v[186:189], v[40:43]
	v_mfma_f32_16x16x32_bf16 v[28:31], v[128:131], v[202:205], v[28:31]
	v_mfma_f32_16x16x32_bf16 v[24:27], v[136:139], v[202:205], v[24:27]
	v_mfma_f32_16x16x32_bf16 v[12:15], v[128:131], v[210:213], v[12:15]
	v_mfma_f32_16x16x32_bf16 v[8:11], v[136:139], v[210:213], v[8:11]
	v_mfma_f32_16x16x32_bf16 v[60:63], v[132:135], v[182:185], v[60:63]
	v_mfma_f32_16x16x32_bf16 v[56:59], v[140:143], v[182:185], v[56:59]
	v_mfma_f32_16x16x32_bf16 v[44:47], v[132:135], v[194:197], v[44:47]
	v_mfma_f32_16x16x32_bf16 v[40:43], v[140:143], v[194:197], v[40:43]
	v_mfma_f32_16x16x32_bf16 v[28:31], v[132:135], v[206:209], v[28:31]
	v_mfma_f32_16x16x32_bf16 v[24:27], v[140:143], v[206:209], v[24:27]
	v_mfma_f32_16x16x32_bf16 v[12:15], v[132:135], v[214:217], v[12:15]
	v_mfma_f32_16x16x32_bf16 v[8:11], v[140:143], v[214:217], v[8:11]
	s_setprio 0
	s_setprio 1
	v_mfma_f32_16x16x32_bf16 v[52:55], v[144:147], v[178:181], v[52:55]
	v_mfma_f32_16x16x32_bf16 v[48:51], v[164:167], v[178:181], v[48:51]
	v_mfma_f32_16x16x32_bf16 v[36:39], v[144:147], v[186:189], v[36:39]
	v_mfma_f32_16x16x32_bf16 v[32:35], v[164:167], v[186:189], v[32:35]
	v_mfma_f32_16x16x32_bf16 v[20:23], v[144:147], v[202:205], v[20:23]
	v_mfma_f32_16x16x32_bf16 v[16:19], v[164:167], v[202:205], v[16:19]
	v_mfma_f32_16x16x32_bf16 v[4:7], v[144:147], v[210:213], v[4:7]
	v_mfma_f32_16x16x32_bf16 v[0:3], v[164:167], v[210:213], v[0:3]
	v_mfma_f32_16x16x32_bf16 v[52:55], v[148:151], v[182:185], v[52:55]
	v_mfma_f32_16x16x32_bf16 v[48:51], v[174:177], v[182:185], v[48:51]
	v_mfma_f32_16x16x32_bf16 v[36:39], v[148:151], v[194:197], v[36:39]
	v_mfma_f32_16x16x32_bf16 v[32:35], v[174:177], v[194:197], v[32:35]
	v_mfma_f32_16x16x32_bf16 v[20:23], v[148:151], v[206:209], v[20:23]
	v_mfma_f32_16x16x32_bf16 v[16:19], v[174:177], v[206:209], v[16:19]
	v_mfma_f32_16x16x32_bf16 v[4:7], v[148:151], v[214:217], v[4:7]
	v_mfma_f32_16x16x32_bf16 v[0:3], v[174:177], v[214:217], v[0:3]
	s_setprio 0
	s_barrier
	s_add_i32 s24, 0, 0x18000
	s_add_i32 s25, 0, 0x1c000
	v_add_u32_e32 v140, 0x18000, v172
	v_add_u32_e32 v174, 0x1c000, v172
	ds_read_b128 v[128:131], v140
	ds_read_b128 v[132:135], v140 offset:1024
	ds_read_b128 v[136:139], v140 offset:2048
	ds_read_b128 v[140:143], v140 offset:3072
	ds_read_b128 v[144:147], v174
	ds_read_b128 v[148:151], v174 offset:1024
	ds_read_b128 v[164:167], v174 offset:2048
	ds_read_b128 v[174:177], v174 offset:3072
	s_add_u32 s42, s42, 0x80000
	s_addc_u32 s43, s43, 0
	s_mov_b32 m0, s49
	v_lshl_add_u64 v[230:231], s[42:43], 0, v[158:159]
	ds_read_b128 v[178:181], v173 offset:32768
	ds_read_b128 v[182:185], v173 offset:33792
	ds_read_b128 v[186:189], v173 offset:34816
	ds_read_b128 v[194:197], v173 offset:35840
	ds_read_b128 v[202:205], v173 offset:36864
	ds_read_b128 v[206:209], v173 offset:37888
	ds_read_b128 v[210:213], v173 offset:38912
	ds_read_b128 v[214:217], v173 offset:39936
	global_load_lds_dwordx4 v[230:231], off
	s_mov_b32 m0, s50
	v_lshl_add_u64 v[230:231], s[42:43], 0, v[154:155]
	global_load_lds_dwordx4 v[230:231], off
	s_waitcnt vmcnt(8)
	s_waitcnt lgkmcnt(0)
	s_barrier
	s_setprio 1
	s_waitcnt lgkmcnt(0)
	v_mfma_f32_16x16x32_bf16 v[124:127], v[128:131], v[178:181], v[124:127]
	v_mfma_f32_16x16x32_bf16 v[120:123], v[136:139], v[178:181], v[120:123]
	v_mfma_f32_16x16x32_bf16 v[108:111], v[128:131], v[186:189], v[108:111]
	v_mfma_f32_16x16x32_bf16 v[104:107], v[136:139], v[186:189], v[104:107]
	v_mfma_f32_16x16x32_bf16 v[92:95], v[128:131], v[202:205], v[92:95]
	v_mfma_f32_16x16x32_bf16 v[88:91], v[136:139], v[202:205], v[88:91]
	v_mfma_f32_16x16x32_bf16 v[76:79], v[128:131], v[210:213], v[76:79]
	v_mfma_f32_16x16x32_bf16 v[72:75], v[136:139], v[210:213], v[72:75]
	v_mfma_f32_16x16x32_bf16 v[124:127], v[132:135], v[182:185], v[124:127]
	v_mfma_f32_16x16x32_bf16 v[120:123], v[140:143], v[182:185], v[120:123]
	v_mfma_f32_16x16x32_bf16 v[108:111], v[132:135], v[194:197], v[108:111]
	v_mfma_f32_16x16x32_bf16 v[104:107], v[140:143], v[194:197], v[104:107]
	v_mfma_f32_16x16x32_bf16 v[92:95], v[132:135], v[206:209], v[92:95]
	v_mfma_f32_16x16x32_bf16 v[88:91], v[140:143], v[206:209], v[88:91]
	v_mfma_f32_16x16x32_bf16 v[76:79], v[132:135], v[214:217], v[76:79]
	v_mfma_f32_16x16x32_bf16 v[72:75], v[140:143], v[214:217], v[72:75]
	s_setprio 0
	s_setprio 1
	v_mfma_f32_16x16x32_bf16 v[116:119], v[144:147], v[178:181], v[116:119]
	v_mfma_f32_16x16x32_bf16 v[112:115], v[164:167], v[178:181], v[112:115]
	v_mfma_f32_16x16x32_bf16 v[100:103], v[144:147], v[186:189], v[100:103]
	v_mfma_f32_16x16x32_bf16 v[96:99], v[164:167], v[186:189], v[96:99]
	v_mfma_f32_16x16x32_bf16 v[84:87], v[144:147], v[202:205], v[84:87]
	v_mfma_f32_16x16x32_bf16 v[80:83], v[164:167], v[202:205], v[80:83]
	v_mfma_f32_16x16x32_bf16 v[68:71], v[144:147], v[210:213], v[68:71]
	v_mfma_f32_16x16x32_bf16 v[64:67], v[164:167], v[210:213], v[64:67]
	v_mfma_f32_16x16x32_bf16 v[116:119], v[148:151], v[182:185], v[116:119]
	v_mfma_f32_16x16x32_bf16 v[112:115], v[174:177], v[182:185], v[112:115]
	v_mfma_f32_16x16x32_bf16 v[100:103], v[148:151], v[194:197], v[100:103]
	v_mfma_f32_16x16x32_bf16 v[96:99], v[174:177], v[194:197], v[96:99]
	v_mfma_f32_16x16x32_bf16 v[84:87], v[148:151], v[206:209], v[84:87]
	v_mfma_f32_16x16x32_bf16 v[80:83], v[174:177], v[206:209], v[80:83]
	v_mfma_f32_16x16x32_bf16 v[68:71], v[148:151], v[214:217], v[68:71]
	v_mfma_f32_16x16x32_bf16 v[64:67], v[174:177], v[214:217], v[64:67]
	s_setprio 0
	s_barrier
; #define PG8_STAGE(bufoff, gbase, voff) do { _Pragma("unroll") for (int _i = 0; _i < 2; ++_i) \
;         __builtin_amdgcn_global_load_lds((const unsigned*)((const char*)(gbase) + (voff)[_i]), (PG8_LAS unsigned*)(lds + (bufoff) + ldsw + _i * 8192), 16, 0, 0); } while (0)
; #define PG8_LDA(dst, b, h) do { _Pragma("unroll") for (int m = 0; m < 4; ++m) _Pragma("unroll") for (int k = 0; k < 2; ++k) dst[m][k] = *(const PG8_LAS bf16x8*)(lds + PG8_SA(b, h) + aoff + m * 2048 + k * 1024); } while (0)
; #define PG8_MMA(ai, bj, At, Bt) do { __builtin_amdgcn_s_setprio(1); _Pragma("unroll") for (int m = 0; m < 4; ++m) _Pragma("unroll") for (int n = 0; n < 2; ++n) _Pragma("unroll") for (int k = 0; k < 2; ++k) \
;         acc[ai][bj][m][n] = __builtin_amdgcn_mfma_f32_16x16x32_bf16(Bt[n][k], At[m][k], acc[ai][bj][m][n], 0, 0, 0); __builtin_amdgcn_s_setprio(0); } while (0)
; #define PG8_WAIT_V(n) asm volatile("s_waitcnt vmcnt(" #n ")" ::: "memory")
; #define PG8_WAIT_L(n) asm volatile("s_waitcnt lgkmcnt(" #n ")" ::: "memory")
; #define PG8_BAR __builtin_amdgcn_s_barrier()
; #define PG8_SCHED __builtin_amdgcn_sched_barrier(0)
; template <class Epi, class Sched, bool ALIGN_EPI = false, bool SP2 = false>
; __device__ __forceinline__ void gemm_phase(PG8_LAS unsigned char* lds, const Gemm g, const Sched& S, const Epi& E) {
;     ...
;         for (int t = 0; t < nt; t += 2) {
;     ...
;             PG8_WAIT_V(8); PG8_WAIT_L(0); PG8_BAR; PG8_MMA(0, 0, At, B0); PG8_MMA(0, 1, At, B1); PG8_BAR; PG8_SCHED;
;             PG8_LDA(At, 1, 1); PG8_STAGE(PG8_SB(1, 0), b3, voffB); PG8_STAGE(PG8_SB(1, 1), b3 + hstep, voffB); PG8_STAGE(PG8_SA(1, 0), a3, voffA);
;             PG8_WAIT_V(8); PG8_WAIT_L(0); PG8_BAR; PG8_MMA(1, 0, At, B0); PG8_MMA(1, 1, At, B1); PG8_BAR; PG8_SCHED;
	s_add_i32 s24, s24, s47
	v_lshl_add_u64 v[168:169], v[168:169], 0, s[16:17]
	s_mov_b32 m0, s24
	ds_read_b128 v[178:181], v173 offset:49152
	ds_read_b128 v[182:185], v173 offset:50176
	ds_read_b128 v[186:189], v173 offset:51200
	ds_read_b128 v[194:197], v173 offset:52224
	ds_read_b128 v[202:205], v173 offset:53248
	ds_read_b128 v[206:209], v173 offset:54272
	ds_read_b128 v[210:213], v173 offset:55296
	ds_read_b128 v[214:217], v173 offset:56320
	global_load_lds_dwordx4 v[168:169], off
	s_add_i32 m0, s24, 0x2000
	s_add_u32 s38, s38, 0x80080
	v_lshl_add_u64 v[168:169], v[190:191], 0, s[16:17]
	s_addc_u32 s39, s39, 0
	s_add_i32 s24, s25, s47
	global_load_lds_dwordx4 v[168:169], off
	s_mov_b32 m0, s24
	v_lshl_add_u64 v[168:169], s[38:39], 0, v[156:157]
	global_load_lds_dwordx4 v[168:169], off
	s_add_i32 m0, s24, 0x2000
	v_lshl_add_u64 v[168:169], s[38:39], 0, v[152:153]
	global_load_lds_dwordx4 v[168:169], off
	s_mov_b32 m0, s55
	v_lshl_add_u64 v[168:169], v[218:219], 0, s[16:17]
	global_load_lds_dwordx4 v[168:169], off
	s_mov_b32 m0, s56
	v_lshl_add_u64 v[168:169], v[220:221], 0, s[16:17]
	global_load_lds_dwordx4 v[168:169], off
	s_waitcnt vmcnt(8)
	s_waitcnt lgkmcnt(0)
	s_barrier
	s_setprio 1
	s_waitcnt lgkmcnt(0)
	v_mfma_f32_16x16x32_bf16 v[60:63], v[128:131], v[178:181], v[60:63]
	v_mfma_f32_16x16x32_bf16 v[56:59], v[136:139], v[178:181], v[56:59]
	v_mfma_f32_16x16x32_bf16 v[44:47], v[128:131], v[186:189], v[44:47]
	v_mfma_f32_16x16x32_bf16 v[40:43], v[136:139], v[186:189], v[40:43]
	v_mfma_f32_16x16x32_bf16 v[28:31], v[128:131], v[202:205], v[28:31]
	v_mfma_f32_16x16x32_bf16 v[24:27], v[136:139], v[202:205], v[24:27]
	v_mfma_f32_16x16x32_bf16 v[12:15], v[128:131], v[210:213], v[12:15]
	v_mfma_f32_16x16x32_bf16 v[8:11], v[136:139], v[210:213], v[8:11]
	v_mfma_f32_16x16x32_bf16 v[60:63], v[132:135], v[182:185], v[60:63]
	v_mfma_f32_16x16x32_bf16 v[56:59], v[140:143], v[182:185], v[56:59]
	v_mfma_f32_16x16x32_bf16 v[44:47], v[132:135], v[194:197], v[44:47]
	v_mfma_f32_16x16x32_bf16 v[40:43], v[140:143], v[194:197], v[40:43]
	v_mfma_f32_16x16x32_bf16 v[28:31], v[132:135], v[206:209], v[28:31]
	v_mfma_f32_16x16x32_bf16 v[24:27], v[140:143], v[206:209], v[24:27]
	v_mfma_f32_16x16x32_bf16 v[12:15], v[132:135], v[214:217], v[12:15]
	v_mfma_f32_16x16x32_bf16 v[8:11], v[140:143], v[214:217], v[8:11]
	s_setprio 0
	s_setprio 1
	v_mfma_f32_16x16x32_bf16 v[52:55], v[144:147], v[178:181], v[52:55]
	v_mfma_f32_16x16x32_bf16 v[48:51], v[164:167], v[178:181], v[48:51]
	v_mfma_f32_16x16x32_bf16 v[36:39], v[144:147], v[186:189], v[36:39]
	v_mfma_f32_16x16x32_bf16 v[32:35], v[164:167], v[186:189], v[32:35]
	v_mfma_f32_16x16x32_bf16 v[20:23], v[144:147], v[202:205], v[20:23]
	v_mfma_f32_16x16x32_bf16 v[16:19], v[164:167], v[202:205], v[16:19]
	v_mfma_f32_16x16x32_bf16 v[4:7], v[144:147], v[210:213], v[4:7]
	v_mfma_f32_16x16x32_bf16 v[0:3], v[164:167], v[210:213], v[0:3]
	v_mfma_f32_16x16x32_bf16 v[52:55], v[148:151], v[182:185], v[52:55]
	v_mfma_f32_16x16x32_bf16 v[48:51], v[174:177], v[182:185], v[48:51]
	v_mfma_f32_16x16x32_bf16 v[36:39], v[148:151], v[194:197], v[36:39]
	v_mfma_f32_16x16x32_bf16 v[32:35], v[174:177], v[194:197], v[32:35]
	v_mfma_f32_16x16x32_bf16 v[20:23], v[148:151], v[206:209], v[20:23]
	v_mfma_f32_16x16x32_bf16 v[16:19], v[174:177], v[206:209], v[16:19]
	v_mfma_f32_16x16x32_bf16 v[4:7], v[148:151], v[214:217], v[4:7]
	v_mfma_f32_16x16x32_bf16 v[0:3], v[174:177], v[214:217], v[0:3]
	s_setprio 0
	s_barrier
	s_add_i32 s65, s65, 2
	s_add_u32 s36, s36, 0x100
	s_addc_u32 s37, s37, 0
	s_add_u32 s63, s63, 0x100
	s_addc_u32 s64, s64, 0
	s_cmp_gt_u32 s65, 29
	s_cbranch_scc0 .LBB0_635
	s_and_b64 vcc, exec, s[10:11]
	s_cbranch_vccz .LBB0_638
	s_barrier

; #define PG8_STAGE(bufoff, gbase, voff) do { _Pragma("unroll") for (int _i = 0; _i < 2; ++_i) \
;         __builtin_amdgcn_global_load_lds((const unsigned*)((const char*)(gbase) + (voff)[_i]), (PG8_LAS unsigned*)(lds + (bufoff) + ldsw + _i * 8192), 16, 0, 0); } while (0)
; #define PG8_LDA(dst, b, h) do { _Pragma("unroll") for (int m = 0; m < 4; ++m) _Pragma("unroll") for (int k = 0; k < 2; ++k) dst[m][k] = *(const PG8_LAS bf16x8*)(lds + PG8_SA(b, h) + aoff + m * 2048 + k * 1024); } while (0)
; #define PG8_LDB(dst, b, h) do { _Pragma("unroll") for (int n = 0; n < 2; ++n) _Pragma("unroll") for (int k = 0; k < 2; ++k) dst[n][k] = *(const PG8_LAS bf16x8*)(lds + PG8_SB(b, h) + boff + n * 2048 + k * 1024); } while (0)
; #define PG8_MMA(ai, bj, At, Bt) do { __builtin_amdgcn_s_setprio(1); _Pragma("unroll") for (int m = 0; m < 4; ++m) _Pragma("unroll") for (int n = 0; n < 2; ++n) _Pragma("unroll") for (int k = 0; k < 2; ++k) \
;         acc[ai][bj][m][n] = __builtin_amdgcn_mfma_f32_16x16x32_bf16(Bt[n][k], At[m][k], acc[ai][bj][m][n], 0, 0, 0); __builtin_amdgcn_s_setprio(0); } while (0)
; #define PG8_WAIT_V(n) asm volatile("s_waitcnt vmcnt(" #n ")" ::: "memory")
; #define PG8_WAIT_L(n) asm volatile("s_waitcnt lgkmcnt(" #n ")" ::: "memory")
; template <class Epi, class Sched, bool ALIGN_EPI = false, bool SP2 = false>
; __device__ __forceinline__ void gemm_phase(PG8_LAS unsigned char* lds, const Gemm g, const Sched& S, const Epi& E) {
;     ...
;             const bool last = (t == nt - 2);
;             const char* a1 = cA + (size_t)(t + 1) * kstep;
;             const char* a2 = last ? nA : cA + (size_t)(t + 2) * kstep; const char* b2 = last ? nB : cB + (size_t)(t + 2) * kstep;
;             const char* a3 = a2 + kstep; const char* b3 = b2 + kstep;
;             if (last && has_next) S.a_ready(nxt);
;             if constexpr (SP2) {
;             PG8_LDB(B0, 0, 0); PG8_LDB(B1, 0, 1); PG8_SCHED; PG8_LDA(At, 0, 0); PG8_STAGE(PG8_SA(1, 1), a1 + hstep, voffA);
;             PG8_WAIT_V(8); PG8_WAIT_L(0); PG8_BAR; PG8_MMA(0, 0, At, B0); PG8_MMA(0, 1, At, B1); PG8_BAR; PG8_SCHED;
;             PG8_LDA(At, 0, 1); PG8_STAGE(PG8_SB(0, 0), b2, voffB); PG8_STAGE(PG8_SB(0, 1), b2 + hstep, voffB); PG8_STAGE(PG8_SA(0, 0), a2, voffA);
;             PG8_WAIT_V(8); PG8_WAIT_L(0); PG8_BAR; PG8_MMA(1, 0, At, B0); PG8_MMA(1, 1, At, B1); PG8_BAR; PG8_SCHED;
.LBB0_730:
	v_add_u32_e32 v148, 0x10000, v151
	ds_read_b128 v[140:143], v148
	ds_read_b128 v[144:147], v148 offset:1024
	ds_read_b128 v[154:157], v148 offset:2048
	ds_read_b128 v[158:161], v148 offset:3072
	v_add_u32_e32 v148, 0x14000, v151
	ds_read_b128 v[162:165], v148
	ds_read_b128 v[166:169], v148 offset:1024
	ds_read_b128 v[170:173], v148 offset:2048
	ds_read_b128 v[174:177], v148 offset:3072
	v_lshl_add_u64 v[190:191], s[0:1], 0, v[136:137]
	s_add_i32 m0, s31, 0xc000
	ds_read_b128 v[178:181], v152
	ds_read_b128 v[182:185], v152 offset:1024
	ds_read_b128 v[186:189], v152 offset:2048
	ds_read_b128 v[194:197], v152 offset:3072
	ds_read_b128 v[202:205], v152 offset:4096
	ds_read_b128 v[206:209], v152 offset:5120
	ds_read_b128 v[210:213], v152 offset:6144
	ds_read_b128 v[214:217], v152 offset:7168
	global_load_lds_dwordx4 v[190:191], off
	s_add_i32 m0, s31, 0xe000
	v_lshl_add_u64 v[190:191], s[0:1], 0, v[138:139]
	global_load_lds_dwordx4 v[190:191], off
	s_add_u32 s10, s0, 0xfff80080
	s_addc_u32 s11, s1, -1
	s_add_i32 s24, 0, 0x10000
	s_cmp_eq_u32 s64, 28
	s_cselect_b32 s13, s49, s11
	s_cselect_b32 s12, s60, s10
	s_cselect_b32 s11, s47, s63
	s_cselect_b32 s10, s61, s62
	s_add_i32 s25, 0, 0x14000
	s_waitcnt vmcnt(8)
	s_waitcnt lgkmcnt(0)
	s_barrier
	s_setprio 1
	s_waitcnt lgkmcnt(0)
	v_mfma_f32_16x16x32_bf16 v[124:127], v[140:143], v[178:181], v[124:127]
	v_mfma_f32_16x16x32_bf16 v[112:115], v[154:157], v[178:181], v[112:115]
	v_mfma_f32_16x16x32_bf16 v[108:111], v[140:143], v[186:189], v[108:111]
	v_mfma_f32_16x16x32_bf16 v[100:103], v[154:157], v[186:189], v[100:103]
	v_mfma_f32_16x16x32_bf16 v[92:95], v[140:143], v[202:205], v[92:95]
	v_mfma_f32_16x16x32_bf16 v[84:87], v[154:157], v[202:205], v[84:87]
	v_mfma_f32_16x16x32_bf16 v[76:79], v[140:143], v[210:213], v[76:79]
	v_mfma_f32_16x16x32_bf16 v[68:71], v[154:157], v[210:213], v[68:71]
	v_mfma_f32_16x16x32_bf16 v[124:127], v[144:147], v[182:185], v[124:127]
	v_mfma_f32_16x16x32_bf16 v[112:115], v[158:161], v[182:185], v[112:115]
	v_mfma_f32_16x16x32_bf16 v[108:111], v[144:147], v[194:197], v[108:111]
	v_mfma_f32_16x16x32_bf16 v[100:103], v[158:161], v[194:197], v[100:103]
	v_mfma_f32_16x16x32_bf16 v[92:95], v[144:147], v[206:209], v[92:95]
	v_mfma_f32_16x16x32_bf16 v[84:87], v[158:161], v[206:209], v[84:87]
	v_mfma_f32_16x16x32_bf16 v[76:79], v[144:147], v[214:217], v[76:79]
	v_mfma_f32_16x16x32_bf16 v[68:71], v[158:161], v[214:217], v[68:71]
	s_setprio 0
	s_setprio 1
	v_mfma_f32_16x16x32_bf16 v[120:123], v[162:165], v[178:181], v[120:123]
	v_mfma_f32_16x16x32_bf16 v[116:119], v[170:173], v[178:181], v[116:119]
	v_mfma_f32_16x16x32_bf16 v[104:107], v[162:165], v[186:189], v[104:107]
	v_mfma_f32_16x16x32_bf16 v[96:99], v[170:173], v[186:189], v[96:99]
	v_mfma_f32_16x16x32_bf16 v[88:91], v[162:165], v[202:205], v[88:91]
	v_mfma_f32_16x16x32_bf16 v[80:83], v[170:173], v[202:205], v[80:83]
	v_mfma_f32_16x16x32_bf16 v[72:75], v[162:165], v[210:213], v[72:75]
	v_mfma_f32_16x16x32_bf16 v[64:67], v[170:173], v[210:213], v[64:67]
	v_mfma_f32_16x16x32_bf16 v[120:123], v[166:169], v[182:185], v[120:123]
	v_mfma_f32_16x16x32_bf16 v[116:119], v[174:177], v[182:185], v[116:119]
	v_mfma_f32_16x16x32_bf16 v[104:107], v[166:169], v[194:197], v[104:107]
	v_mfma_f32_16x16x32_bf16 v[96:99], v[174:177], v[194:197], v[96:99]
	v_mfma_f32_16x16x32_bf16 v[88:91], v[166:169], v[206:209], v[88:91]
	v_mfma_f32_16x16x32_bf16 v[80:83], v[174:177], v[206:209], v[80:83]
	v_mfma_f32_16x16x32_bf16 v[72:75], v[166:169], v[214:217], v[72:75]
	v_mfma_f32_16x16x32_bf16 v[64:67], v[174:177], v[214:217], v[64:67]
	s_setprio 0
	s_barrier
	s_add_i32 s24, s24, s30
	v_lshl_add_u64 v[190:191], s[10:11], 0, v[132:133]
	s_mov_b32 m0, s24
	ds_read_b128 v[178:181], v152 offset:16384
	ds_read_b128 v[182:185], v152 offset:17408
	ds_read_b128 v[186:189], v152 offset:18432
	ds_read_b128 v[194:197], v152 offset:19456
	ds_read_b128 v[202:205], v152 offset:20480
	ds_read_b128 v[206:209], v152 offset:21504
	ds_read_b128 v[210:213], v152 offset:22528
	ds_read_b128 v[214:217], v152 offset:23552
	global_load_lds_dwordx4 v[190:191], off
	s_add_i32 m0, s24, 0x2000
	s_add_u32 s66, s10, 0x80000
	v_lshl_add_u64 v[218:219], s[10:11], 0, v[128:129]
	s_addc_u32 s67, s11, 0
	s_add_i32 s24, s25, s30
	global_load_lds_dwordx4 v[218:219], off
	v_lshl_add_u64 v[220:221], s[66:67], 0, v[132:133]
	s_mov_b32 m0, s24
	v_lshl_add_u64 v[230:231], s[12:13], 0, v[130:131]
	global_load_lds_dwordx4 v[220:221], off
	s_add_i32 m0, s24, 0x2000
	v_lshl_add_u64 v[220:221], s[66:67], 0, v[128:129]
	global_load_lds_dwordx4 v[220:221], off
	s_mov_b32 m0, s31
	v_lshl_add_u64 v[220:221], s[12:13], 0, v[134:135]
	global_load_lds_dwordx4 v[220:221], off
	s_mov_b32 m0, s34
	s_nop 0
	global_load_lds_dwordx4 v[230:231], off
	s_waitcnt vmcnt(8)
	s_waitcnt lgkmcnt(0)
	s_barrier
; #define PG8_STAGE(bufoff, gbase, voff) do { _Pragma("unroll") for (int _i = 0; _i < 2; ++_i) \
;         __builtin_amdgcn_global_load_lds((const unsigned*)((const char*)(gbase) + (voff)[_i]), (PG8_LAS unsigned*)(lds + (bufoff) + ldsw + _i * 8192), 16, 0, 0); } while (0)
; #define PG8_LDA(dst, b, h) do { _Pragma("unroll") for (int m = 0; m < 4; ++m) _Pragma("unroll") for (int k = 0; k < 2; ++k) dst[m][k] = *(const PG8_LAS bf16x8*)(lds + PG8_SA(b, h) + aoff + m * 2048 + k * 1024); } while (0)
; #define PG8_LDB(dst, b, h) do { _Pragma("unroll") for (int n = 0; n < 2; ++n) _Pragma("unroll") for (int k = 0; k < 2; ++k) dst[n][k] = *(const PG8_LAS bf16x8*)(lds + PG8_SB(b, h) + boff + n * 2048 + k * 1024); } while (0)
; #define PG8_MMA(ai, bj, At, Bt) do { __builtin_amdgcn_s_setprio(1); _Pragma("unroll") for (int m = 0; m < 4; ++m) _Pragma("unroll") for (int n = 0; n < 2; ++n) _Pragma("unroll") for (int k = 0; k < 2; ++k) \
;         acc[ai][bj][m][n] = __builtin_amdgcn_mfma_f32_16x16x32_bf16(Bt[n][k], At[m][k], acc[ai][bj][m][n], 0, 0, 0); __builtin_amdgcn_s_setprio(0); } while (0)
; #define PG8_WAIT_V(n) asm volatile("s_waitcnt vmcnt(" #n ")" ::: "memory")
; #define PG8_WAIT_L(n) asm volatile("s_waitcnt lgkmcnt(" #n ")" ::: "memory")
; #define PG8_BAR __builtin_amdgcn_s_barrier()
; #define PG8_SCHED __builtin_amdgcn_sched_barrier(0)
; template <class Epi, class Sched, bool ALIGN_EPI = false, bool SP2 = false>
; __device__ __forceinline__ void gemm_phase(PG8_LAS unsigned char* lds, const Gemm g, const Sched& S, const Epi& E) {
;     ...
;             PG8_LDA(At, 0, 1); PG8_STAGE(PG8_SB(0, 0), b2, voffB); PG8_STAGE(PG8_SB(0, 1), b2 + hstep, voffB); PG8_STAGE(PG8_SA(0, 0), a2, voffA);
;             PG8_WAIT_V(8); PG8_WAIT_L(0); PG8_BAR; PG8_MMA(1, 0, At, B0); PG8_MMA(1, 1, At, B1); PG8_BAR; PG8_SCHED;
;             PG8_LDB(B0, 1, 0); PG8_LDB(B1, 1, 1); PG8_SCHED; PG8_LDA(At, 1, 0); PG8_STAGE(PG8_SA(0, 1), a2 + hstep, voffA);
;             PG8_WAIT_V(8); PG8_WAIT_L(0); PG8_BAR; PG8_MMA(0, 0, At, B0); PG8_MMA(0, 1, At, B1); PG8_BAR; PG8_SCHED;
;             PG8_LDA(At, 1, 1); PG8_STAGE(PG8_SB(1, 0), b3, voffB); PG8_STAGE(PG8_SB(1, 1), b3 + hstep, voffB); PG8_STAGE(PG8_SA(1, 0), a3, voffA);
	s_setprio 1
	s_waitcnt lgkmcnt(0)
	v_mfma_f32_16x16x32_bf16 v[60:63], v[140:143], v[178:181], v[60:63]
	v_mfma_f32_16x16x32_bf16 v[52:55], v[154:157], v[178:181], v[52:55]
	v_mfma_f32_16x16x32_bf16 v[44:47], v[140:143], v[186:189], v[44:47]
	v_mfma_f32_16x16x32_bf16 v[36:39], v[154:157], v[186:189], v[36:39]
	v_mfma_f32_16x16x32_bf16 v[28:31], v[140:143], v[202:205], v[28:31]
	v_mfma_f32_16x16x32_bf16 v[20:23], v[154:157], v[202:205], v[20:23]
	v_mfma_f32_16x16x32_bf16 v[12:15], v[140:143], v[210:213], v[12:15]
	v_mfma_f32_16x16x32_bf16 v[4:7], v[154:157], v[210:213], v[4:7]
	v_mfma_f32_16x16x32_bf16 v[60:63], v[144:147], v[182:185], v[60:63]
	v_mfma_f32_16x16x32_bf16 v[52:55], v[158:161], v[182:185], v[52:55]
	v_mfma_f32_16x16x32_bf16 v[44:47], v[144:147], v[194:197], v[44:47]
	v_mfma_f32_16x16x32_bf16 v[36:39], v[158:161], v[194:197], v[36:39]
	v_mfma_f32_16x16x32_bf16 v[28:31], v[144:147], v[206:209], v[28:31]
	v_mfma_f32_16x16x32_bf16 v[20:23], v[158:161], v[206:209], v[20:23]
	v_mfma_f32_16x16x32_bf16 v[12:15], v[144:147], v[214:217], v[12:15]
	v_mfma_f32_16x16x32_bf16 v[4:7], v[158:161], v[214:217], v[4:7]
	s_setprio 0
	s_setprio 1
	v_mfma_f32_16x16x32_bf16 v[56:59], v[162:165], v[178:181], v[56:59]
	v_mfma_f32_16x16x32_bf16 v[48:51], v[170:173], v[178:181], v[48:51]
	v_mfma_f32_16x16x32_bf16 v[40:43], v[162:165], v[186:189], v[40:43]
	v_mfma_f32_16x16x32_bf16 v[32:35], v[170:173], v[186:189], v[32:35]
	v_mfma_f32_16x16x32_bf16 v[24:27], v[162:165], v[202:205], v[24:27]
	v_mfma_f32_16x16x32_bf16 v[16:19], v[170:173], v[202:205], v[16:19]
	v_mfma_f32_16x16x32_bf16 v[8:11], v[162:165], v[210:213], v[8:11]
	v_mfma_f32_16x16x32_bf16 v[0:3], v[170:173], v[210:213], v[0:3]
	v_mfma_f32_16x16x32_bf16 v[56:59], v[166:169], v[182:185], v[56:59]
	v_mfma_f32_16x16x32_bf16 v[48:51], v[174:177], v[182:185], v[48:51]
	v_mfma_f32_16x16x32_bf16 v[40:43], v[166:169], v[194:197], v[40:43]
	v_mfma_f32_16x16x32_bf16 v[32:35], v[174:177], v[194:197], v[32:35]
	v_mfma_f32_16x16x32_bf16 v[24:27], v[166:169], v[206:209], v[24:27]
	v_mfma_f32_16x16x32_bf16 v[16:19], v[174:177], v[206:209], v[16:19]
	v_mfma_f32_16x16x32_bf16 v[8:11], v[166:169], v[214:217], v[8:11]
	v_mfma_f32_16x16x32_bf16 v[0:3], v[174:177], v[214:217], v[0:3]
	s_setprio 0
	s_barrier
	s_add_i32 s24, 0, 0x18000
	v_add_u32_e32 v148, 0x18000, v151
	s_add_i32 s25, 0, 0x1c000
	ds_read_b128 v[140:143], v148
	ds_read_b128 v[144:147], v148 offset:1024
	ds_read_b128 v[154:157], v148 offset:2048
	ds_read_b128 v[158:161], v148 offset:3072
	v_add_u32_e32 v148, 0x1c000, v151
	ds_read_b128 v[162:165], v148
	ds_read_b128 v[166:169], v148 offset:1024
	ds_read_b128 v[170:173], v148 offset:2048
	ds_read_b128 v[174:177], v148 offset:3072
	s_add_u32 s12, s12, 0x80000
	s_addc_u32 s13, s13, 0
	s_mov_b32 m0, s36
	v_lshl_add_u64 v[232:233], s[12:13], 0, v[134:135]
	ds_read_b128 v[178:181], v152 offset:32768
	ds_read_b128 v[182:185], v152 offset:33792
	ds_read_b128 v[186:189], v152 offset:34816
	ds_read_b128 v[194:197], v152 offset:35840
	ds_read_b128 v[202:205], v152 offset:36864
	ds_read_b128 v[206:209], v152 offset:37888
	ds_read_b128 v[210:213], v152 offset:38912
	ds_read_b128 v[214:217], v152 offset:39936
	global_load_lds_dwordx4 v[232:233], off
	s_mov_b32 m0, s37
	v_lshl_add_u64 v[232:233], s[12:13], 0, v[130:131]
	global_load_lds_dwordx4 v[232:233], off
	s_waitcnt vmcnt(8)
	s_waitcnt lgkmcnt(0)
	s_barrier
	s_setprio 1
	s_waitcnt lgkmcnt(0)
	v_mfma_f32_16x16x32_bf16 v[124:127], v[140:143], v[178:181], v[124:127]
	v_mfma_f32_16x16x32_bf16 v[112:115], v[154:157], v[178:181], v[112:115]
	v_mfma_f32_16x16x32_bf16 v[108:111], v[140:143], v[186:189], v[108:111]
	v_mfma_f32_16x16x32_bf16 v[100:103], v[154:157], v[186:189], v[100:103]
	v_mfma_f32_16x16x32_bf16 v[92:95], v[140:143], v[202:205], v[92:95]
	v_mfma_f32_16x16x32_bf16 v[84:87], v[154:157], v[202:205], v[84:87]
	v_mfma_f32_16x16x32_bf16 v[76:79], v[140:143], v[210:213], v[76:79]
	v_mfma_f32_16x16x32_bf16 v[68:71], v[154:157], v[210:213], v[68:71]
	v_mfma_f32_16x16x32_bf16 v[124:127], v[144:147], v[182:185], v[124:127]
	v_mfma_f32_16x16x32_bf16 v[112:115], v[158:161], v[182:185], v[112:115]
	v_mfma_f32_16x16x32_bf16 v[108:111], v[144:147], v[194:197], v[108:111]
	v_mfma_f32_16x16x32_bf16 v[100:103], v[158:161], v[194:197], v[100:103]
	v_mfma_f32_16x16x32_bf16 v[92:95], v[144:147], v[206:209], v[92:95]
	v_mfma_f32_16x16x32_bf16 v[84:87], v[158:161], v[206:209], v[84:87]
	v_mfma_f32_16x16x32_bf16 v[76:79], v[144:147], v[214:217], v[76:79]
	v_mfma_f32_16x16x32_bf16 v[68:71], v[158:161], v[214:217], v[68:71]
	s_setprio 0
	s_setprio 1
	v_mfma_f32_16x16x32_bf16 v[120:123], v[162:165], v[178:181], v[120:123]
	v_mfma_f32_16x16x32_bf16 v[116:119], v[170:173], v[178:181], v[116:119]
	v_mfma_f32_16x16x32_bf16 v[104:107], v[162:165], v[186:189], v[104:107]
	v_mfma_f32_16x16x32_bf16 v[96:99], v[170:173], v[186:189], v[96:99]
	v_mfma_f32_16x16x32_bf16 v[88:91], v[162:165], v[202:205], v[88:91]
	v_mfma_f32_16x16x32_bf16 v[80:83], v[170:173], v[202:205], v[80:83]
	v_mfma_f32_16x16x32_bf16 v[72:75], v[162:165], v[210:213], v[72:75]
	v_mfma_f32_16x16x32_bf16 v[64:67], v[170:173], v[210:213], v[64:67]
	v_mfma_f32_16x16x32_bf16 v[120:123], v[166:169], v[182:185], v[120:123]
	v_mfma_f32_16x16x32_bf16 v[116:119], v[174:177], v[182:185], v[116:119]
	v_mfma_f32_16x16x32_bf16 v[104:107], v[166:169], v[194:197], v[104:107]
	v_mfma_f32_16x16x32_bf16 v[96:99], v[174:177], v[194:197], v[96:99]
	v_mfma_f32_16x16x32_bf16 v[88:91], v[166:169], v[206:209], v[88:91]
	v_mfma_f32_16x16x32_bf16 v[80:83], v[174:177], v[206:209], v[80:83]
	v_mfma_f32_16x16x32_bf16 v[72:75], v[166:169], v[214:217], v[72:75]
	v_mfma_f32_16x16x32_bf16 v[64:67], v[174:177], v[214:217], v[64:67]
	s_setprio 0
	s_barrier
; #define PG8_STAGE(bufoff, gbase, voff) do { _Pragma("unroll") for (int _i = 0; _i < 2; ++_i) \
;         __builtin_amdgcn_global_load_lds((const unsigned*)((const char*)(gbase) + (voff)[_i]), (PG8_LAS unsigned*)(lds + (bufoff) + ldsw + _i * 8192), 16, 0, 0); } while (0)
; #define PG8_LDA(dst, b, h) do { _Pragma("unroll") for (int m = 0; m < 4; ++m) _Pragma("unroll") for (int k = 0; k < 2; ++k) dst[m][k] = *(const PG8_LAS bf16x8*)(lds + PG8_SA(b, h) + aoff + m * 2048 + k * 1024); } while (0)
; #define PG8_MMA(ai, bj, At, Bt) do { __builtin_amdgcn_s_setprio(1); _Pragma("unroll") for (int m = 0; m < 4; ++m) _Pragma("unroll") for (int n = 0; n < 2; ++n) _Pragma("unroll") for (int k = 0; k < 2; ++k) \
;         acc[ai][bj][m][n] = __builtin_amdgcn_mfma_f32_16x16x32_bf16(Bt[n][k], At[m][k], acc[ai][bj][m][n], 0, 0, 0); __builtin_amdgcn_s_setprio(0); } while (0)
; #define PG8_WAIT_V(n) asm volatile("s_waitcnt vmcnt(" #n ")" ::: "memory")
; #define PG8_WAIT_L(n) asm volatile("s_waitcnt lgkmcnt(" #n ")" ::: "memory")
; #define PG8_BAR __builtin_amdgcn_s_barrier()
; #define PG8_SCHED __builtin_amdgcn_sched_barrier(0)
; template <class Epi, class Sched, bool ALIGN_EPI = false, bool SP2 = false>
; __device__ __forceinline__ void gemm_phase(PG8_LAS unsigned char* lds, const Gemm g, const Sched& S, const Epi& E) {
;     ...
;         for (int t = 0; t < nt; t += 2) {
;     ...
;             PG8_WAIT_V(8); PG8_WAIT_L(0); PG8_BAR; PG8_MMA(0, 0, At, B0); PG8_MMA(0, 1, At, B1); PG8_BAR; PG8_SCHED;
;             PG8_LDA(At, 1, 1); PG8_STAGE(PG8_SB(1, 0), b3, voffB); PG8_STAGE(PG8_SB(1, 1), b3 + hstep, voffB); PG8_STAGE(PG8_SA(1, 0), a3, voffA);
;             PG8_WAIT_V(8); PG8_WAIT_L(0); PG8_BAR; PG8_MMA(1, 0, At, B0); PG8_MMA(1, 1, At, B1); PG8_BAR; PG8_SCHED;
	s_add_i32 s12, s24, s30
	v_lshl_add_u64 v[190:191], v[190:191], 0, s[16:17]
	s_mov_b32 m0, s12
	ds_read_b128 v[178:181], v152 offset:49152
	ds_read_b128 v[182:185], v152 offset:50176
	ds_read_b128 v[186:189], v152 offset:51200
	ds_read_b128 v[194:197], v152 offset:52224
	ds_read_b128 v[202:205], v152 offset:53248
	ds_read_b128 v[206:209], v152 offset:54272
	ds_read_b128 v[210:213], v152 offset:55296
	ds_read_b128 v[214:217], v152 offset:56320
	global_load_lds_dwordx4 v[190:191], off
	s_add_i32 m0, s12, 0x2000
	s_add_u32 s10, s10, 0x80080
	v_lshl_add_u64 v[190:191], v[218:219], 0, s[16:17]
	s_addc_u32 s11, s11, 0
	s_add_i32 s12, s25, s30
	global_load_lds_dwordx4 v[190:191], off
	s_mov_b32 m0, s12
	v_lshl_add_u64 v[190:191], s[10:11], 0, v[132:133]
	global_load_lds_dwordx4 v[190:191], off
	s_add_i32 m0, s12, 0x2000
	v_lshl_add_u64 v[190:191], s[10:11], 0, v[128:129]
	global_load_lds_dwordx4 v[190:191], off
	s_mov_b32 m0, s56
	v_lshl_add_u64 v[190:191], v[220:221], 0, s[16:17]
	global_load_lds_dwordx4 v[190:191], off
	s_mov_b32 m0, s57
	v_lshl_add_u64 v[190:191], v[230:231], 0, s[16:17]
	global_load_lds_dwordx4 v[190:191], off
	s_waitcnt vmcnt(8)
	s_waitcnt lgkmcnt(0)
	s_barrier
	s_setprio 1
	s_waitcnt lgkmcnt(0)
	v_mfma_f32_16x16x32_bf16 v[60:63], v[140:143], v[178:181], v[60:63]
	v_mfma_f32_16x16x32_bf16 v[52:55], v[154:157], v[178:181], v[52:55]
	v_mfma_f32_16x16x32_bf16 v[44:47], v[140:143], v[186:189], v[44:47]
	v_mfma_f32_16x16x32_bf16 v[36:39], v[154:157], v[186:189], v[36:39]
	v_mfma_f32_16x16x32_bf16 v[28:31], v[140:143], v[202:205], v[28:31]
	v_mfma_f32_16x16x32_bf16 v[20:23], v[154:157], v[202:205], v[20:23]
	v_mfma_f32_16x16x32_bf16 v[12:15], v[140:143], v[210:213], v[12:15]
	v_mfma_f32_16x16x32_bf16 v[4:7], v[154:157], v[210:213], v[4:7]
	v_mfma_f32_16x16x32_bf16 v[60:63], v[144:147], v[182:185], v[60:63]
	v_mfma_f32_16x16x32_bf16 v[52:55], v[158:161], v[182:185], v[52:55]
	v_mfma_f32_16x16x32_bf16 v[44:47], v[144:147], v[194:197], v[44:47]
	v_mfma_f32_16x16x32_bf16 v[36:39], v[158:161], v[194:197], v[36:39]
	v_mfma_f32_16x16x32_bf16 v[28:31], v[144:147], v[206:209], v[28:31]
	v_mfma_f32_16x16x32_bf16 v[20:23], v[158:161], v[206:209], v[20:23]
	v_mfma_f32_16x16x32_bf16 v[12:15], v[144:147], v[214:217], v[12:15]
	v_mfma_f32_16x16x32_bf16 v[4:7], v[158:161], v[214:217], v[4:7]
	s_setprio 0
	s_setprio 1
	v_mfma_f32_16x16x32_bf16 v[56:59], v[162:165], v[178:181], v[56:59]
	v_mfma_f32_16x16x32_bf16 v[48:51], v[170:173], v[178:181], v[48:51]
	v_mfma_f32_16x16x32_bf16 v[40:43], v[162:165], v[186:189], v[40:43]
	v_mfma_f32_16x16x32_bf16 v[32:35], v[170:173], v[186:189], v[32:35]
	v_mfma_f32_16x16x32_bf16 v[24:27], v[162:165], v[202:205], v[24:27]
	v_mfma_f32_16x16x32_bf16 v[16:19], v[170:173], v[202:205], v[16:19]
	v_mfma_f32_16x16x32_bf16 v[8:11], v[162:165], v[210:213], v[8:11]
	v_mfma_f32_16x16x32_bf16 v[0:3], v[170:173], v[210:213], v[0:3]
	v_mfma_f32_16x16x32_bf16 v[56:59], v[166:169], v[182:185], v[56:59]
	v_mfma_f32_16x16x32_bf16 v[48:51], v[174:177], v[182:185], v[48:51]
	v_mfma_f32_16x16x32_bf16 v[40:43], v[166:169], v[194:197], v[40:43]
	v_mfma_f32_16x16x32_bf16 v[32:35], v[174:177], v[194:197], v[32:35]
	v_mfma_f32_16x16x32_bf16 v[24:27], v[166:169], v[206:209], v[24:27]
	v_mfma_f32_16x16x32_bf16 v[16:19], v[174:177], v[206:209], v[16:19]
	v_mfma_f32_16x16x32_bf16 v[8:11], v[166:169], v[214:217], v[8:11]
	v_mfma_f32_16x16x32_bf16 v[0:3], v[174:177], v[214:217], v[0:3]
	s_setprio 0
	s_barrier
	s_add_i32 s64, s64, 2
	s_add_u32 s0, s0, 0x100
	s_addc_u32 s1, s1, 0
	s_add_u32 s62, s62, 0x100
	s_addc_u32 s63, s63, 0
	s_cmp_gt_u32 s64, 29
	s_cbranch_scc0 .LBB0_730
	s_and_b64 vcc, exec, s[44:45]
	s_cbranch_vccz .LBB0_733
	s_barrier

; #define PG8_STAGE(bufoff, gbase, voff) do { _Pragma("unroll") for (int _i = 0; _i < 2; ++_i) \
;         __builtin_amdgcn_global_load_lds((const unsigned*)((const char*)(gbase) + (voff)[_i]), (PG8_LAS unsigned*)(lds + (bufoff) + ldsw + _i * 8192), 16, 0, 0); } while (0)
; #define PG8_LDA(dst, b, h) do { _Pragma("unroll") for (int m = 0; m < 4; ++m) _Pragma("unroll") for (int k = 0; k < 2; ++k) dst[m][k] = *(const PG8_LAS bf16x8*)(lds + PG8_SA(b, h) + aoff + m * 2048 + k * 1024); } while (0)
; #define PG8_LDB(dst, b, h) do { _Pragma("unroll") for (int n = 0; n < 2; ++n) _Pragma("unroll") for (int k = 0; k < 2; ++k) dst[n][k] = *(const PG8_LAS bf16x8*)(lds + PG8_SB(b, h) + boff + n * 2048 + k * 1024); } while (0)
; #define PG8_MMA(ai, bj, At, Bt) do { __builtin_amdgcn_s_setprio(1); _Pragma("unroll") for (int m = 0; m < 4; ++m) _Pragma("unroll") for (int n = 0; n < 2; ++n) _Pragma("unroll") for (int k = 0; k < 2; ++k) \
;         acc[ai][bj][m][n] = __builtin_amdgcn_mfma_f32_16x16x32_bf16(Bt[n][k], At[m][k], acc[ai][bj][m][n], 0, 0, 0); __builtin_amdgcn_s_setprio(0); } while (0)
; #define PG8_WAIT_V(n) asm volatile("s_waitcnt vmcnt(" #n ")" ::: "memory")
; #define PG8_WAIT_L(n) asm volatile("s_waitcnt lgkmcnt(" #n ")" ::: "memory")
; template <class Epi, class Sched, bool ALIGN_EPI = false, bool SP2 = false>
; __device__ __forceinline__ void gemm_phase(PG8_LAS unsigned char* lds, const Gemm g, const Sched& S, const Epi& E) {
;     ...
;             const bool last = (t == nt - 2);
;             const char* a1 = cA + (size_t)(t + 1) * kstep;
;             const char* a2 = last ? nA : cA + (size_t)(t + 2) * kstep; const char* b2 = last ? nB : cB + (size_t)(t + 2) * kstep;
;             const char* a3 = a2 + kstep; const char* b3 = b2 + kstep;
;             if (last && has_next) S.a_ready(nxt);
;             if constexpr (SP2) {
;             PG8_LDB(B0, 0, 0); PG8_LDB(B1, 0, 1); PG8_SCHED; PG8_LDA(At, 0, 0); PG8_STAGE(PG8_SA(1, 1), a1 + hstep, voffA);
;             PG8_WAIT_V(8); PG8_WAIT_L(0); PG8_BAR; PG8_MMA(0, 0, At, B0); PG8_MMA(0, 1, At, B1); PG8_BAR; PG8_SCHED;
;             PG8_LDA(At, 0, 1); PG8_STAGE(PG8_SB(0, 0), b2, voffB); PG8_STAGE(PG8_SB(0, 1), b2 + hstep, voffB); PG8_STAGE(PG8_SA(0, 0), a2, voffA);
;             PG8_WAIT_V(8); PG8_WAIT_L(0); PG8_BAR; PG8_MMA(1, 0, At, B0); PG8_MMA(1, 1, At, B1); PG8_BAR; PG8_SCHED;
.LBB0_817:
	v_add_u32_e32 v140, 0x10000, v172
	v_add_u32_e32 v168, 0x14000, v172
	ds_read_b128 v[128:131], v140
	ds_read_b128 v[132:135], v140 offset:1024
	ds_read_b128 v[136:139], v140 offset:2048
	ds_read_b128 v[140:143], v140 offset:3072
	ds_read_b128 v[144:147], v168
	ds_read_b128 v[148:151], v168 offset:1024
	ds_read_b128 v[164:167], v168 offset:2048
	ds_read_b128 v[174:177], v168 offset:3072
	v_lshl_add_u64 v[168:169], s[18:19], 0, v[160:161]
	s_add_i32 m0, s2, 0xc000
	ds_read_b128 v[178:181], v173
	ds_read_b128 v[182:185], v173 offset:1024
	ds_read_b128 v[186:189], v173 offset:2048
	ds_read_b128 v[194:197], v173 offset:3072
	ds_read_b128 v[202:205], v173 offset:4096
	ds_read_b128 v[206:209], v173 offset:5120
	ds_read_b128 v[210:213], v173 offset:6144
	ds_read_b128 v[214:217], v173 offset:7168
	global_load_lds_dwordx4 v[168:169], off
	s_add_i32 m0, s2, 0xe000
	v_lshl_add_u64 v[168:169], s[18:19], 0, v[162:163]
	global_load_lds_dwordx4 v[168:169], off
	s_add_u32 s30, s18, 0x100
	s_addc_u32 s31, s19, 0
	s_add_i32 s24, 0, 0x10000
	s_cmpk_eq_i32 s61, 0x54
	s_cselect_b32 s39, s5, s31
	s_cselect_b32 s38, s4, s30
	s_cselect_b32 s37, s15, s60
	s_cselect_b32 s36, s14, s59
	s_add_i32 s25, 0, 0x14000
	s_waitcnt vmcnt(8)
	s_waitcnt lgkmcnt(0)
	s_barrier
	s_setprio 1
	s_waitcnt lgkmcnt(0)
	v_mfma_f32_16x16x32_bf16 v[124:127], v[128:131], v[178:181], v[124:127]
	v_mfma_f32_16x16x32_bf16 v[120:123], v[136:139], v[178:181], v[120:123]
	v_mfma_f32_16x16x32_bf16 v[108:111], v[128:131], v[186:189], v[108:111]
	v_mfma_f32_16x16x32_bf16 v[104:107], v[136:139], v[186:189], v[104:107]
	v_mfma_f32_16x16x32_bf16 v[92:95], v[128:131], v[202:205], v[92:95]
	v_mfma_f32_16x16x32_bf16 v[88:91], v[136:139], v[202:205], v[88:91]
	v_mfma_f32_16x16x32_bf16 v[76:79], v[128:131], v[210:213], v[76:79]
	v_mfma_f32_16x16x32_bf16 v[72:75], v[136:139], v[210:213], v[72:75]
	v_mfma_f32_16x16x32_bf16 v[124:127], v[132:135], v[182:185], v[124:127]
	v_mfma_f32_16x16x32_bf16 v[120:123], v[140:143], v[182:185], v[120:123]
	v_mfma_f32_16x16x32_bf16 v[108:111], v[132:135], v[194:197], v[108:111]
	v_mfma_f32_16x16x32_bf16 v[104:107], v[140:143], v[194:197], v[104:107]
	v_mfma_f32_16x16x32_bf16 v[92:95], v[132:135], v[206:209], v[92:95]
	v_mfma_f32_16x16x32_bf16 v[88:91], v[140:143], v[206:209], v[88:91]
	v_mfma_f32_16x16x32_bf16 v[76:79], v[132:135], v[214:217], v[76:79]
	v_mfma_f32_16x16x32_bf16 v[72:75], v[140:143], v[214:217], v[72:75]
	s_setprio 0
	s_setprio 1
	v_mfma_f32_16x16x32_bf16 v[116:119], v[144:147], v[178:181], v[116:119]
	v_mfma_f32_16x16x32_bf16 v[112:115], v[164:167], v[178:181], v[112:115]
	v_mfma_f32_16x16x32_bf16 v[100:103], v[144:147], v[186:189], v[100:103]
	v_mfma_f32_16x16x32_bf16 v[96:99], v[164:167], v[186:189], v[96:99]
	v_mfma_f32_16x16x32_bf16 v[84:87], v[144:147], v[202:205], v[84:87]
	v_mfma_f32_16x16x32_bf16 v[80:83], v[164:167], v[202:205], v[80:83]
	v_mfma_f32_16x16x32_bf16 v[68:71], v[144:147], v[210:213], v[68:71]
	v_mfma_f32_16x16x32_bf16 v[64:67], v[164:167], v[210:213], v[64:67]
	v_mfma_f32_16x16x32_bf16 v[116:119], v[148:151], v[182:185], v[116:119]
	v_mfma_f32_16x16x32_bf16 v[112:115], v[174:177], v[182:185], v[112:115]
	v_mfma_f32_16x16x32_bf16 v[100:103], v[148:151], v[194:197], v[100:103]
	v_mfma_f32_16x16x32_bf16 v[96:99], v[174:177], v[194:197], v[96:99]
	v_mfma_f32_16x16x32_bf16 v[84:87], v[148:151], v[206:209], v[84:87]
	v_mfma_f32_16x16x32_bf16 v[80:83], v[174:177], v[206:209], v[80:83]
	v_mfma_f32_16x16x32_bf16 v[68:71], v[148:151], v[214:217], v[68:71]
	v_mfma_f32_16x16x32_bf16 v[64:67], v[174:177], v[214:217], v[64:67]
	s_setprio 0
	s_barrier
	s_add_i32 s18, s24, s43
	v_lshl_add_u64 v[168:169], s[36:37], 0, v[156:157]
	s_mov_b32 m0, s18
	ds_read_b128 v[178:181], v173 offset:16384
	ds_read_b128 v[182:185], v173 offset:17408
	ds_read_b128 v[186:189], v173 offset:18432
	ds_read_b128 v[194:197], v173 offset:19456
	ds_read_b128 v[202:205], v173 offset:20480
	ds_read_b128 v[206:209], v173 offset:21504
	ds_read_b128 v[210:213], v173 offset:22528
	ds_read_b128 v[214:217], v173 offset:23552
	global_load_lds_dwordx4 v[168:169], off
	s_add_i32 m0, s18, 0x2000
	s_add_u32 s18, s36, 0x160000
	v_lshl_add_u64 v[190:191], s[36:37], 0, v[152:153]
	s_addc_u32 s19, s37, 0
	s_add_i32 s24, s25, s43
	global_load_lds_dwordx4 v[190:191], off
	v_lshl_add_u64 v[218:219], s[18:19], 0, v[156:157]
	s_mov_b32 m0, s24
	v_lshl_add_u64 v[220:221], s[38:39], 0, v[154:155]
	global_load_lds_dwordx4 v[218:219], off
	s_add_i32 m0, s24, 0x2000
	v_lshl_add_u64 v[218:219], s[18:19], 0, v[152:153]
	global_load_lds_dwordx4 v[218:219], off
	s_mov_b32 m0, s2
	v_lshl_add_u64 v[218:219], s[38:39], 0, v[158:159]
	global_load_lds_dwordx4 v[218:219], off
	s_mov_b32 m0, s44
	s_nop 0
	global_load_lds_dwordx4 v[220:221], off
	s_waitcnt vmcnt(8)
	s_waitcnt lgkmcnt(0)
	s_barrier
; #define PG8_STAGE(bufoff, gbase, voff) do { _Pragma("unroll") for (int _i = 0; _i < 2; ++_i) \
;         __builtin_amdgcn_global_load_lds((const unsigned*)((const char*)(gbase) + (voff)[_i]), (PG8_LAS unsigned*)(lds + (bufoff) + ldsw + _i * 8192), 16, 0, 0); } while (0)
; #define PG8_LDA(dst, b, h) do { _Pragma("unroll") for (int m = 0; m < 4; ++m) _Pragma("unroll") for (int k = 0; k < 2; ++k) dst[m][k] = *(const PG8_LAS bf16x8*)(lds + PG8_SA(b, h) + aoff + m * 2048 + k * 1024); } while (0)
; #define PG8_LDB(dst, b, h) do { _Pragma("unroll") for (int n = 0; n < 2; ++n) _Pragma("unroll") for (int k = 0; k < 2; ++k) dst[n][k] = *(const PG8_LAS bf16x8*)(lds + PG8_SB(b, h) + boff + n * 2048 + k * 1024); } while (0)
; #define PG8_MMA(ai, bj, At, Bt) do { __builtin_amdgcn_s_setprio(1); _Pragma("unroll") for (int m = 0; m < 4; ++m) _Pragma("unroll") for (int n = 0; n < 2; ++n) _Pragma("unroll") for (int k = 0; k < 2; ++k) \
;         acc[ai][bj][m][n] = __builtin_amdgcn_mfma_f32_16x16x32_bf16(Bt[n][k], At[m][k], acc[ai][bj][m][n], 0, 0, 0); __builtin_amdgcn_s_setprio(0); } while (0)
; #define PG8_WAIT_V(n) asm volatile("s_waitcnt vmcnt(" #n ")" ::: "memory")
; #define PG8_WAIT_L(n) asm volatile("s_waitcnt lgkmcnt(" #n ")" ::: "memory")
; #define PG8_BAR __builtin_amdgcn_s_barrier()
; #define PG8_SCHED __builtin_amdgcn_sched_barrier(0)
; template <class Epi, class Sched, bool ALIGN_EPI = false, bool SP2 = false>
; __device__ __forceinline__ void gemm_phase(PG8_LAS unsigned char* lds, const Gemm g, const Sched& S, const Epi& E) {
;     ...
;             PG8_LDA(At, 0, 1); PG8_STAGE(PG8_SB(0, 0), b2, voffB); PG8_STAGE(PG8_SB(0, 1), b2 + hstep, voffB); PG8_STAGE(PG8_SA(0, 0), a2, voffA);
;             PG8_WAIT_V(8); PG8_WAIT_L(0); PG8_BAR; PG8_MMA(1, 0, At, B0); PG8_MMA(1, 1, At, B1); PG8_BAR; PG8_SCHED;
;             PG8_LDB(B0, 1, 0); PG8_LDB(B1, 1, 1); PG8_SCHED; PG8_LDA(At, 1, 0); PG8_STAGE(PG8_SA(0, 1), a2 + hstep, voffA);
;             PG8_WAIT_V(8); PG8_WAIT_L(0); PG8_BAR; PG8_MMA(0, 0, At, B0); PG8_MMA(0, 1, At, B1); PG8_BAR; PG8_SCHED;
;             PG8_LDA(At, 1, 1); PG8_STAGE(PG8_SB(1, 0), b3, voffB); PG8_STAGE(PG8_SB(1, 1), b3 + hstep, voffB); PG8_STAGE(PG8_SA(1, 0), a3, voffA);
	s_setprio 1
	s_waitcnt lgkmcnt(0)
	v_mfma_f32_16x16x32_bf16 v[60:63], v[128:131], v[178:181], v[60:63]
	v_mfma_f32_16x16x32_bf16 v[56:59], v[136:139], v[178:181], v[56:59]
	v_mfma_f32_16x16x32_bf16 v[44:47], v[128:131], v[186:189], v[44:47]
	v_mfma_f32_16x16x32_bf16 v[40:43], v[136:139], v[186:189], v[40:43]
	v_mfma_f32_16x16x32_bf16 v[28:31], v[128:131], v[202:205], v[28:31]
	v_mfma_f32_16x16x32_bf16 v[24:27], v[136:139], v[202:205], v[24:27]
	v_mfma_f32_16x16x32_bf16 v[12:15], v[128:131], v[210:213], v[12:15]
	v_mfma_f32_16x16x32_bf16 v[8:11], v[136:139], v[210:213], v[8:11]
	v_mfma_f32_16x16x32_bf16 v[60:63], v[132:135], v[182:185], v[60:63]
	v_mfma_f32_16x16x32_bf16 v[56:59], v[140:143], v[182:185], v[56:59]
	v_mfma_f32_16x16x32_bf16 v[44:47], v[132:135], v[194:197], v[44:47]
	v_mfma_f32_16x16x32_bf16 v[40:43], v[140:143], v[194:197], v[40:43]
	v_mfma_f32_16x16x32_bf16 v[28:31], v[132:135], v[206:209], v[28:31]
	v_mfma_f32_16x16x32_bf16 v[24:27], v[140:143], v[206:209], v[24:27]
	v_mfma_f32_16x16x32_bf16 v[12:15], v[132:135], v[214:217], v[12:15]
	v_mfma_f32_16x16x32_bf16 v[8:11], v[140:143], v[214:217], v[8:11]
	s_setprio 0
	s_setprio 1
	v_mfma_f32_16x16x32_bf16 v[52:55], v[144:147], v[178:181], v[52:55]
	v_mfma_f32_16x16x32_bf16 v[48:51], v[164:167], v[178:181], v[48:51]
	v_mfma_f32_16x16x32_bf16 v[36:39], v[144:147], v[186:189], v[36:39]
	v_mfma_f32_16x16x32_bf16 v[32:35], v[164:167], v[186:189], v[32:35]
	v_mfma_f32_16x16x32_bf16 v[20:23], v[144:147], v[202:205], v[20:23]
	v_mfma_f32_16x16x32_bf16 v[16:19], v[164:167], v[202:205], v[16:19]
	v_mfma_f32_16x16x32_bf16 v[4:7], v[144:147], v[210:213], v[4:7]
	v_mfma_f32_16x16x32_bf16 v[0:3], v[164:167], v[210:213], v[0:3]
	v_mfma_f32_16x16x32_bf16 v[52:55], v[148:151], v[182:185], v[52:55]
	v_mfma_f32_16x16x32_bf16 v[48:51], v[174:177], v[182:185], v[48:51]
	v_mfma_f32_16x16x32_bf16 v[36:39], v[148:151], v[194:197], v[36:39]
	v_mfma_f32_16x16x32_bf16 v[32:35], v[174:177], v[194:197], v[32:35]
	v_mfma_f32_16x16x32_bf16 v[20:23], v[148:151], v[206:209], v[20:23]
	v_mfma_f32_16x16x32_bf16 v[16:19], v[174:177], v[206:209], v[16:19]
	v_mfma_f32_16x16x32_bf16 v[4:7], v[148:151], v[214:217], v[4:7]
	v_mfma_f32_16x16x32_bf16 v[0:3], v[174:177], v[214:217], v[0:3]
	s_setprio 0
	s_barrier
	s_add_i32 s24, 0, 0x18000
	s_add_i32 s25, 0, 0x1c000
	v_add_u32_e32 v140, 0x18000, v172
	v_add_u32_e32 v174, 0x1c000, v172
	ds_read_b128 v[128:131], v140
	ds_read_b128 v[132:135], v140 offset:1024
	ds_read_b128 v[136:139], v140 offset:2048
	ds_read_b128 v[140:143], v140 offset:3072
	ds_read_b128 v[144:147], v174
	ds_read_b128 v[148:151], v174 offset:1024
	ds_read_b128 v[164:167], v174 offset:2048
	ds_read_b128 v[174:177], v174 offset:3072
	s_add_u32 s18, s38, 0x160000
	s_addc_u32 s19, s39, 0
	s_mov_b32 m0, s45
	v_lshl_add_u64 v[230:231], s[18:19], 0, v[158:159]
	ds_read_b128 v[178:181], v173 offset:32768
	ds_read_b128 v[182:185], v173 offset:33792
	ds_read_b128 v[186:189], v173 offset:34816
	ds_read_b128 v[194:197], v173 offset:35840
	ds_read_b128 v[202:205], v173 offset:36864
	ds_read_b128 v[206:209], v173 offset:37888
	ds_read_b128 v[210:213], v173 offset:38912
	ds_read_b128 v[214:217], v173 offset:39936
	global_load_lds_dwordx4 v[230:231], off
	s_mov_b32 m0, s46
	v_lshl_add_u64 v[230:231], s[18:19], 0, v[154:155]
	global_load_lds_dwordx4 v[230:231], off
	s_waitcnt vmcnt(8)
	s_waitcnt lgkmcnt(0)
	s_barrier
	s_setprio 1
	s_waitcnt lgkmcnt(0)
	v_mfma_f32_16x16x32_bf16 v[124:127], v[128:131], v[178:181], v[124:127]
	v_mfma_f32_16x16x32_bf16 v[120:123], v[136:139], v[178:181], v[120:123]
	v_mfma_f32_16x16x32_bf16 v[108:111], v[128:131], v[186:189], v[108:111]
	v_mfma_f32_16x16x32_bf16 v[104:107], v[136:139], v[186:189], v[104:107]
	v_mfma_f32_16x16x32_bf16 v[92:95], v[128:131], v[202:205], v[92:95]
	v_mfma_f32_16x16x32_bf16 v[88:91], v[136:139], v[202:205], v[88:91]
	v_mfma_f32_16x16x32_bf16 v[76:79], v[128:131], v[210:213], v[76:79]
	v_mfma_f32_16x16x32_bf16 v[72:75], v[136:139], v[210:213], v[72:75]
	v_mfma_f32_16x16x32_bf16 v[124:127], v[132:135], v[182:185], v[124:127]
	v_mfma_f32_16x16x32_bf16 v[120:123], v[140:143], v[182:185], v[120:123]
	v_mfma_f32_16x16x32_bf16 v[108:111], v[132:135], v[194:197], v[108:111]
	v_mfma_f32_16x16x32_bf16 v[104:107], v[140:143], v[194:197], v[104:107]
	v_mfma_f32_16x16x32_bf16 v[92:95], v[132:135], v[206:209], v[92:95]
	v_mfma_f32_16x16x32_bf16 v[88:91], v[140:143], v[206:209], v[88:91]
	v_mfma_f32_16x16x32_bf16 v[76:79], v[132:135], v[214:217], v[76:79]
	v_mfma_f32_16x16x32_bf16 v[72:75], v[140:143], v[214:217], v[72:75]
	s_setprio 0
	s_setprio 1
	v_mfma_f32_16x16x32_bf16 v[116:119], v[144:147], v[178:181], v[116:119]
	v_mfma_f32_16x16x32_bf16 v[112:115], v[164:167], v[178:181], v[112:115]
	v_mfma_f32_16x16x32_bf16 v[100:103], v[144:147], v[186:189], v[100:103]
	v_mfma_f32_16x16x32_bf16 v[96:99], v[164:167], v[186:189], v[96:99]
	v_mfma_f32_16x16x32_bf16 v[84:87], v[144:147], v[202:205], v[84:87]
	v_mfma_f32_16x16x32_bf16 v[80:83], v[164:167], v[202:205], v[80:83]
	v_mfma_f32_16x16x32_bf16 v[68:71], v[144:147], v[210:213], v[68:71]
	v_mfma_f32_16x16x32_bf16 v[64:67], v[164:167], v[210:213], v[64:67]
	v_mfma_f32_16x16x32_bf16 v[116:119], v[148:151], v[182:185], v[116:119]
	v_mfma_f32_16x16x32_bf16 v[112:115], v[174:177], v[182:185], v[112:115]
	v_mfma_f32_16x16x32_bf16 v[100:103], v[148:151], v[194:197], v[100:103]
	v_mfma_f32_16x16x32_bf16 v[96:99], v[174:177], v[194:197], v[96:99]
	v_mfma_f32_16x16x32_bf16 v[84:87], v[148:151], v[206:209], v[84:87]
	v_mfma_f32_16x16x32_bf16 v[80:83], v[174:177], v[206:209], v[80:83]
	v_mfma_f32_16x16x32_bf16 v[68:71], v[148:151], v[214:217], v[68:71]
	v_mfma_f32_16x16x32_bf16 v[64:67], v[174:177], v[214:217], v[64:67]
	s_setprio 0
	s_barrier
; #define PG8_STAGE(bufoff, gbase, voff) do { _Pragma("unroll") for (int _i = 0; _i < 2; ++_i) \
;         __builtin_amdgcn_global_load_lds((const unsigned*)((const char*)(gbase) + (voff)[_i]), (PG8_LAS unsigned*)(lds + (bufoff) + ldsw + _i * 8192), 16, 0, 0); } while (0)
; #define PG8_LDA(dst, b, h) do { _Pragma("unroll") for (int m = 0; m < 4; ++m) _Pragma("unroll") for (int k = 0; k < 2; ++k) dst[m][k] = *(const PG8_LAS bf16x8*)(lds + PG8_SA(b, h) + aoff + m * 2048 + k * 1024); } while (0)
; #define PG8_MMA(ai, bj, At, Bt) do { __builtin_amdgcn_s_setprio(1); _Pragma("unroll") for (int m = 0; m < 4; ++m) _Pragma("unroll") for (int n = 0; n < 2; ++n) _Pragma("unroll") for (int k = 0; k < 2; ++k) \
;         acc[ai][bj][m][n] = __builtin_amdgcn_mfma_f32_16x16x32_bf16(Bt[n][k], At[m][k], acc[ai][bj][m][n], 0, 0, 0); __builtin_amdgcn_s_setprio(0); } while (0)
; #define PG8_WAIT_V(n) asm volatile("s_waitcnt vmcnt(" #n ")" ::: "memory")
; #define PG8_WAIT_L(n) asm volatile("s_waitcnt lgkmcnt(" #n ")" ::: "memory")
; #define PG8_BAR __builtin_amdgcn_s_barrier()
; #define PG8_SCHED __builtin_amdgcn_sched_barrier(0)
; template <class Epi, class Sched, bool ALIGN_EPI = false, bool SP2 = false>
; __device__ __forceinline__ void gemm_phase(PG8_LAS unsigned char* lds, const Gemm g, const Sched& S, const Epi& E) {
;     ...
;         for (int t = 0; t < nt; t += 2) {
;     ...
;             PG8_WAIT_V(8); PG8_WAIT_L(0); PG8_BAR; PG8_MMA(0, 0, At, B0); PG8_MMA(0, 1, At, B1); PG8_BAR; PG8_SCHED;
;             PG8_LDA(At, 1, 1); PG8_STAGE(PG8_SB(1, 0), b3, voffB); PG8_STAGE(PG8_SB(1, 1), b3 + hstep, voffB); PG8_STAGE(PG8_SA(1, 0), a3, voffA);
;             PG8_WAIT_V(8); PG8_WAIT_L(0); PG8_BAR; PG8_MMA(1, 0, At, B0); PG8_MMA(1, 1, At, B1); PG8_BAR; PG8_SCHED;
	s_add_i32 s18, s24, s43
	v_lshl_add_u64 v[168:169], v[168:169], 0, s[16:17]
	s_mov_b32 m0, s18
	ds_read_b128 v[178:181], v173 offset:49152
	ds_read_b128 v[182:185], v173 offset:50176
	ds_read_b128 v[186:189], v173 offset:51200
	ds_read_b128 v[194:197], v173 offset:52224
	ds_read_b128 v[202:205], v173 offset:53248
	ds_read_b128 v[206:209], v173 offset:54272
	ds_read_b128 v[210:213], v173 offset:55296
	ds_read_b128 v[214:217], v173 offset:56320
	global_load_lds_dwordx4 v[168:169], off
	s_add_i32 m0, s18, 0x2000
	s_add_u32 s18, s36, 0x160080
	v_lshl_add_u64 v[168:169], v[190:191], 0, s[16:17]
	s_addc_u32 s19, s37, 0
	s_add_i32 s24, s25, s43
	global_load_lds_dwordx4 v[168:169], off
	s_mov_b32 m0, s24
	v_lshl_add_u64 v[168:169], s[18:19], 0, v[156:157]
	global_load_lds_dwordx4 v[168:169], off
	s_add_i32 m0, s24, 0x2000
	v_lshl_add_u64 v[168:169], s[18:19], 0, v[152:153]
	global_load_lds_dwordx4 v[168:169], off
	s_mov_b32 m0, s51
	v_lshl_add_u64 v[168:169], v[218:219], 0, s[16:17]
	global_load_lds_dwordx4 v[168:169], off
	s_mov_b32 m0, s52
	v_lshl_add_u64 v[168:169], v[220:221], 0, s[16:17]
	global_load_lds_dwordx4 v[168:169], off
	s_waitcnt vmcnt(8)
	s_waitcnt lgkmcnt(0)
	s_barrier
	s_setprio 1
	s_waitcnt lgkmcnt(0)
	v_mfma_f32_16x16x32_bf16 v[60:63], v[128:131], v[178:181], v[60:63]
	v_mfma_f32_16x16x32_bf16 v[56:59], v[136:139], v[178:181], v[56:59]
	v_mfma_f32_16x16x32_bf16 v[44:47], v[128:131], v[186:189], v[44:47]
	v_mfma_f32_16x16x32_bf16 v[40:43], v[136:139], v[186:189], v[40:43]
	v_mfma_f32_16x16x32_bf16 v[28:31], v[128:131], v[202:205], v[28:31]
	v_mfma_f32_16x16x32_bf16 v[24:27], v[136:139], v[202:205], v[24:27]
	v_mfma_f32_16x16x32_bf16 v[12:15], v[128:131], v[210:213], v[12:15]
	v_mfma_f32_16x16x32_bf16 v[8:11], v[136:139], v[210:213], v[8:11]
	v_mfma_f32_16x16x32_bf16 v[60:63], v[132:135], v[182:185], v[60:63]
	v_mfma_f32_16x16x32_bf16 v[56:59], v[140:143], v[182:185], v[56:59]
	v_mfma_f32_16x16x32_bf16 v[44:47], v[132:135], v[194:197], v[44:47]
	v_mfma_f32_16x16x32_bf16 v[40:43], v[140:143], v[194:197], v[40:43]
	v_mfma_f32_16x16x32_bf16 v[28:31], v[132:135], v[206:209], v[28:31]
	v_mfma_f32_16x16x32_bf16 v[24:27], v[140:143], v[206:209], v[24:27]
	v_mfma_f32_16x16x32_bf16 v[12:15], v[132:135], v[214:217], v[12:15]
	v_mfma_f32_16x16x32_bf16 v[8:11], v[140:143], v[214:217], v[8:11]
	s_setprio 0
	s_setprio 1
	v_mfma_f32_16x16x32_bf16 v[52:55], v[144:147], v[178:181], v[52:55]
	v_mfma_f32_16x16x32_bf16 v[48:51], v[164:167], v[178:181], v[48:51]
	v_mfma_f32_16x16x32_bf16 v[36:39], v[144:147], v[186:189], v[36:39]
	v_mfma_f32_16x16x32_bf16 v[32:35], v[164:167], v[186:189], v[32:35]
	v_mfma_f32_16x16x32_bf16 v[20:23], v[144:147], v[202:205], v[20:23]
	v_mfma_f32_16x16x32_bf16 v[16:19], v[164:167], v[202:205], v[16:19]
	v_mfma_f32_16x16x32_bf16 v[4:7], v[144:147], v[210:213], v[4:7]
	v_mfma_f32_16x16x32_bf16 v[0:3], v[164:167], v[210:213], v[0:3]
	v_mfma_f32_16x16x32_bf16 v[52:55], v[148:151], v[182:185], v[52:55]
	v_mfma_f32_16x16x32_bf16 v[48:51], v[174:177], v[182:185], v[48:51]
	v_mfma_f32_16x16x32_bf16 v[36:39], v[148:151], v[194:197], v[36:39]
	v_mfma_f32_16x16x32_bf16 v[32:35], v[174:177], v[194:197], v[32:35]
	v_mfma_f32_16x16x32_bf16 v[20:23], v[148:151], v[206:209], v[20:23]
	v_mfma_f32_16x16x32_bf16 v[16:19], v[174:177], v[206:209], v[16:19]
	v_mfma_f32_16x16x32_bf16 v[4:7], v[148:151], v[214:217], v[4:7]
	v_mfma_f32_16x16x32_bf16 v[0:3], v[174:177], v[214:217], v[0:3]
	s_setprio 0
	s_barrier
	s_add_i32 s61, s61, 2
	s_add_u32 s59, s59, 0x100
	s_addc_u32 s60, s60, 0
	s_cmpk_gt_u32 s61, 0x55
	s_mov_b64 s[18:19], s[30:31]
	s_cbranch_scc0 .LBB0_817
	s_and_b64 vcc, exec, s[12:13]
	s_cbranch_vccz .LBB0_820
	s_barrier
